# speedup vs baseline: 1.0153x; 1.0042x over previous
; __device__ __forceinline__ float bflo(unsigned w) { return __uint_as_float(w << 16); }
; __device__ __forceinline__ float bfhi(unsigned w) { return __uint_as_float(w & 0xffff0000u); }
; #define AISSUE(k0, soff) do { const char* kb_ = (const char*)Kn + (size_t)(k0) * 4096; const char* rb_ = (const char*)Kr + (size_t)(k0) * 1024; \
;     char* st_ = lds + (soff) + tid * 16; \
;     GLDS(kb_ + vkn0, st_ + KOFF); GLDS(kb_ + vkn1, st_ + KOFF + 8192); GLDS(rb_ + vkr, st_ + KOFF + KROPE_OFF); \
;     GLDS(kb_ + vv0, st_); GLDS(kb_ + vv1, st_ + 8192); } while (0)
; __device__ __forceinline__ void attn_body(const u16* __restrict__ Qb, const u16* __restrict__ Kn, const u16* __restrict__ Kr,
;                                           u16* __restrict__ Ob, char* lds, int tid, const float* __restrict__ gq_, const float* __restrict__ tab_, int qpos0, float negM) {
;     ...
;   { int sl = tid;        int row = sl >> 4, c = (sl & 15) ^ (row & 15);        vkn0 = (unsigned)(row * 4096 + c * 16);
;     sl = tid + 512;      row = sl >> 4;     c = (sl & 15) ^ (row & 15);        vkn1 = (unsigned)(row * 4096 + c * 16);
;     row = tid >> 3;      c = (tid & 7) ^ ((row >> 1) & 7);                     vkr  = (unsigned)(row * 1024 + c * 16);
; #pragma unroll
;     for (int i = 0; i < 2; ++i) { const int o = (tid + i * 512) * 16, sub = o >> 9, within = o & 511;
;       const int kk = (sub >> 2) * 8 + (within >> 6), cc = (sub & 3) * 32 + ((within & 63) >> 1);
;       const int k = (kk & ~0xC) | ((kk & 4) << 1) | ((kk & 8) >> 1);
;       const unsigned v = (unsigned)(k * 4096 + cc * 2 + 256);
;       if (i == 0) vv0 = v; else vv1 = v; } }
;   constexpr int STG = 40960, KOFF = 16384;
;     ...
;   AISSUE(0, 0);
;   {
;     const char* Qw = (const char*)Qb + (unsigned)(((wid * 32 + r32) * 1536 + hi * 8) * 2);
;     u32x4 qw[12];
; #pragma unroll
;     for (int d0 = 0; d0 < 12; ++d0) qw[d0] = *reinterpret_cast<const u32x4*>(Qw + d0 * 32);
;     float ss = 0.f;
; #pragma unroll
;     for (int d0 = 0; d0 < 12; ++d0)
; #pragma unroll
;       for (int e = 0; e < 4; ++e) { const float a = bflo(qw[d0][e]), b = bfhi(qw[d0][e]); ss += a * a + b * b; }
.LBB0_718:
	s_lshl_b32 s87, s3, 4
	s_lshl_b32 s0, s71, 10
	s_and_b32 s80, s0, 0x7e00000
	s_lshl_b32 s0, s71, 12
	v_mbcnt_lo_u32_b32 v96, -1, 0
	v_mbcnt_hi_u32_b32 v96, -1, v96
	s_and_b32 s79, s0, 0x1f800000
	v_or_b32_e32 v210, s3, v96
	s_lshl_b32 s0, s56, 8
	v_ashrrev_i32_e32 v20, 1, v210
	s_and_b32 s54, s0, 0x1f800
	s_mul_i32 s48, s56, 0xc0000
	v_bfi_b32 v66, s76, v20, v96
	s_mul_hi_u32 s49, s0, 0xc00
	s_add_u32 s50, s57, s48
	v_bfe_u32 v207, v96, 5, 1
	v_mul_lo_u32 v21, v66, s72
	s_addc_u32 s51, s58, s49
	v_lshl_or_b32 v67, v207, 4, v21
	s_barrier
	v_lshlrev_b32_e32 v211, 4, v210
	v_bfe_u32 v23, v210, 2, 2
	v_lshrrev_b32_e32 v28, 1, v210
	v_and_or_b32 v23, v28, 8, v23
	v_lshlrev_b32_e32 v28, 1, v210
	v_and_b32_e32 v29, 48, v211
	v_and_or_b32 v38, v28, s73, v29
	v_bfe_i32 v28, v210, 4, 24
	v_and_b32_e32 v29, 0xffff0, v28
	v_lshrrev_b32_e32 v28, 1, v28
	v_and_b32_e32 v28, 4, v28
	v_or3_b32 v28, v29, v28, v23
	v_lshlrev_b32_e32 v36, 12, v28
	v_add_u32_e32 v50, 0x2000, v211
	v_ashrrev_i32_e32 v33, 8, v50
	v_ashrrev_i32_e32 v16, 4, v210
	v_add_u32_e32 v18, 0x200, v210
	v_and_b32_e32 v34, 0xffff0, v33
	v_lshrrev_b32_e32 v33, 1, v33
	v_xor_b32_e32 v17, v16, v96
	v_ashrrev_i32_e32 v18, 4, v18
	v_and_b32_e32 v33, 4, v33
	v_lshlrev_b32_e32 v17, 4, v17
	v_xor_b32_e32 v19, v18, v96
	v_or3_b32 v23, v34, v33, v23
	v_lshlrev_b32_e32 v16, 12, v16
	v_lshlrev_b32_e32 v19, 4, v19
	v_lshlrev_b32_e32 v21, 7, v210
	v_or_b32_e32 v32, 0x100, v38
	v_lshlrev_b32_e32 v23, 12, v23
	v_and_or_b32 v176, v17, s74, v16
	v_lshlrev_b32_e32 v16, 12, v18
	v_bitop3_b32 v22, v211, v96, s3 bitop3:0x1e
	v_or_b32_e32 v80, v36, v32
	v_or_b32_e32 v81, v23, v32
	v_and_or_b32 v32, v19, s74, v16
	v_and_b32_e32 v16, 0xfffffc00, v21
	s_lshl_b32 s48, s54, 12
	v_and_or_b32 v34, v22, s75, v16
	v_add_u32_e32 v16, 0x4000, v211
	s_add_u32 s48, s61, s48
	v_readfirstlane_b32 s82, v16
	v_add_u32_e32 v16, 0x6000, v211
	s_addc_u32 s49, s62, 0
	s_lshl_b32 s54, s54, 10
	s_mov_b32 m0, s82
	v_readfirstlane_b32 s82, v16
	v_add_u32_e32 v16, 0x8000, v211
	s_add_u32 s54, s65, s54
	global_load_lds_dwordx4 v176, s[48:49]
	s_mov_b32 m0, s82
	v_readfirstlane_b32 s82, v16
	s_addc_u32 s55, s66, 0
	global_load_lds_dwordx4 v32, s[48:49]
	v_mov_b32_e32 v35, v177
	s_mov_b32 m0, s82
	v_or_b32_e32 v36, v38, v36
	v_mov_b32_e32 v37, v177
	v_lshl_add_u64 v[40:41], s[54:55], 0, v[34:35]
	global_load_lds_dwordx4 v34, s[54:55]
	v_lshl_add_u64 v[16:17], s[48:49], 0, v[36:37]
	v_readfirstlane_b32 s54, v211
	v_lshl_add_u64 v[16:17], v[16:17], 0, s[4:5]
	s_mov_b32 m0, s54
	v_or_b32_e32 v38, v38, v23
	v_mov_b32_e32 v39, v177
	global_load_lds_dwordx4 v[16:17], off
	v_lshl_add_u64 v[16:17], s[48:49], 0, v[38:39]
	v_readfirstlane_b32 s54, v50
	v_lshl_add_u64 v[16:17], v[16:17], 0, s[4:5]
	s_mov_b32 m0, s54
	v_and_b32_e32 v208, 0xffffffe0, v20
	global_load_lds_dwordx4 v[16:17], off
	s_nop 0
	s_waitcnt vmcnt(0)
	v_mov_b32_e32 v24, v128
	v_mov_b32_e32 v25, v129
	v_mov_b32_e32 v26, v130
	v_mov_b32_e32 v27, v131
	v_mov_b32_e32 v28, v132
	v_mov_b32_e32 v29, v133
	v_mov_b32_e32 v30, v134
	v_mov_b32_e32 v31, v135
	v_mov_b32_e32 v42, v136
	v_mov_b32_e32 v43, v137
	v_mov_b32_e32 v44, v138
	v_mov_b32_e32 v45, v139
	v_mov_b32_e32 v46, v140
	v_mov_b32_e32 v47, v141
	v_mov_b32_e32 v48, v142
	v_mov_b32_e32 v49, v143
	v_mov_b32_e32 v50, v144
	v_mov_b32_e32 v51, v145
	v_mov_b32_e32 v52, v146
	v_mov_b32_e32 v53, v147
	v_mov_b32_e32 v54, v148
	v_mov_b32_e32 v55, v149
	v_mov_b32_e32 v56, v150
	v_mov_b32_e32 v57, v151
	v_mov_b32_e32 v58, v152
	v_mov_b32_e32 v59, v153
	v_mov_b32_e32 v60, v154
	v_mov_b32_e32 v61, v155
	v_mov_b32_e32 v62, v156
	v_mov_b32_e32 v63, v157
	v_mov_b32_e32 v64, v158
	v_mov_b32_e32 v65, v159
	v_mov_b32_e32 v16, v160
	v_mov_b32_e32 v17, v161
	v_mov_b32_e32 v18, v162
	v_mov_b32_e32 v19, v163
	v_mov_b32_e32 v68, v164
	v_mov_b32_e32 v69, v165
	v_mov_b32_e32 v70, v166
	v_mov_b32_e32 v71, v167
	v_mov_b32_e32 v20, v168
	v_mov_b32_e32 v21, v169
	v_mov_b32_e32 v22, v170
	v_mov_b32_e32 v23, v171
	v_mov_b32_e32 v72, v172
	v_mov_b32_e32 v73, v173
	v_mov_b32_e32 v74, v174
	v_mov_b32_e32 v75, v175
	v_and_b32_e32 v133, 0xffff0000, v24
	v_and_b32_e32 v155, 0xffff0000, v25
	v_lshlrev_b32_e32 v132, 16, v24
	v_mul_f32_e32 v24, v133, v133
	v_lshlrev_b32_e32 v154, 16, v25
	v_mul_f32_e32 v25, v155, v155
	v_fmac_f32_e32 v24, v132, v132
	v_fmac_f32_e32 v25, v154, v154
	v_and_b32_e32 v163, 0xffff0000, v26
	v_add_f32_e32 v24, v24, v25
	v_lshlrev_b32_e32 v162, 16, v26
	v_mul_f32_e32 v25, v163, v163
	v_fmac_f32_e32 v25, v162, v162
	v_and_b32_e32 v165, 0xffff0000, v27
	v_add_f32_e32 v24, v25, v24
	v_lshlrev_b32_e32 v164, 16, v27
	v_mul_f32_e32 v25, v165, v165
	v_fmac_f32_e32 v25, v164, v164
	v_and_b32_e32 v167, 0xffff0000, v28
	v_add_f32_e32 v24, v25, v24
	v_lshlrev_b32_e32 v166, 16, v28
	v_mul_f32_e32 v25, v167, v167
	v_fmac_f32_e32 v25, v166, v166
	v_and_b32_e32 v169, 0xffff0000, v29
	v_add_f32_e32 v24, v25, v24
	v_lshlrev_b32_e32 v168, 16, v29
	v_mul_f32_e32 v25, v169, v169
	v_fmac_f32_e32 v25, v168, v168
	v_and_b32_e32 v125, 0xffff0000, v30
	v_add_f32_e32 v24, v25, v24
	v_lshlrev_b32_e32 v126, 16, v30
	v_mul_f32_e32 v25, v125, v125
	v_fmac_f32_e32 v25, v126, v126
	v_and_b32_e32 v127, 0xffff0000, v31
	v_add_f32_e32 v24, v25, v24
	v_lshlrev_b32_e32 v170, 16, v31
	v_mul_f32_e32 v25, v127, v127
	v_fmac_f32_e32 v25, v170, v170
	v_and_b32_e32 v172, 0xffff0000, v42
	v_add_f32_e32 v24, v25, v24
	v_lshlrev_b32_e32 v171, 16, v42
	v_mul_f32_e32 v25, v172, v172
	v_fmac_f32_e32 v25, v171, v171
	v_and_b32_e32 v174, 0xffff0000, v43
	v_add_f32_e32 v24, v25, v24
	v_lshlrev_b32_e32 v173, 16, v43
	v_mul_f32_e32 v25, v174, v174
	v_fmac_f32_e32 v25, v173, v173
; __device__ __forceinline__ void attn_body(const u16* __restrict__ Qb, const u16* __restrict__ Kn, const u16* __restrict__ Kr,
;                                           u16* __restrict__ Ob, char* lds, int tid, const float* __restrict__ gq_, const float* __restrict__ tab_, int qpos0, float negM) {
;     ...
;     for (int d0 = 0; d0 < 12; ++d0)
; #pragma unroll
;       for (int e = 0; e < 4; ++e) { const float a = bflo(qw[d0][e]), b = bfhi(qw[d0][e]); ss += a * a + b * b; }
;     { auto rr = __builtin_amdgcn_permlane32_swap(__float_as_uint(ss), __float_as_uint(ss), false, false);
;       ss = __uint_as_float(rr[0]) + __uint_as_float(rr[1]); }
;     const float rq = rsqrtf(ss * (1.f / 192.f) + EPS) * QSCALE;
;     const float* gq = gq_ + hi * 8;
; #pragma unroll
;     for (int d0 = 0; d0 < 8; ++d0) {
;       const f32x4 g0 = *reinterpret_cast<const f32x4*>(gq + d0 * 16), g1 = *reinterpret_cast<const f32x4*>(gq + d0 * 16 + 4);
;       const u32x4 w = qw[d0];
;       const u32x4 o = {cvtpk(bflo(w[0]) * rq * g0[0], bfhi(w[0]) * rq * g0[1]), cvtpk(bflo(w[1]) * rq * g0[2], bfhi(w[1]) * rq * g0[3]),
;                        cvtpk(bflo(w[2]) * rq * g1[0], bfhi(w[2]) * rq * g1[1]), cvtpk(bflo(w[3]) * rq * g1[2], bfhi(w[3]) * rq * g1[3])};
;       qr[d0] = *reinterpret_cast<const bf16x8*>(&o); }
;     const float* tcp = tab_ + (size_t)(qpos0 + wid * 32 + r32) * 32 + hi * 8; const float* tsp = tcp + SEQ * 32;
; #pragma unroll
;     for (int dd = 0; dd < 2; ++dd) {
;       float x1[8], x2[8], c_[8], s_[8];
;       { const f32x4 ga = *reinterpret_cast<const f32x4*>(gq + 128 + dd * 16), gb = *reinterpret_cast<const f32x4*>(gq + 128 + dd * 16 + 4);
;         const f32x4 gc = *reinterpret_cast<const f32x4*>(gq + 160 + dd * 16), gd = *reinterpret_cast<const f32x4*>(gq + 160 + dd * 16 + 4);
;         const f32x4 ca = *reinterpret_cast<const f32x4*>(tcp + dd * 16), cb = *reinterpret_cast<const f32x4*>(tcp + dd * 16 + 4);
;         const f32x4 sa = *reinterpret_cast<const f32x4*>(tsp + dd * 16), sb = *reinterpret_cast<const f32x4*>(tsp + dd * 16 + 4);
;         const u32x4 w1 = qw[8 + dd], w2 = qw[10 + dd];
; #pragma unroll
;         for (int e = 0; e < 4; ++e) {
;           const float g1lo = e < 2 ? ga[2 * e] : gb[2 * e - 4], g1hi = e < 2 ? ga[2 * e + 1] : gb[2 * e - 3];
;           const float g2lo = e < 2 ? gc[2 * e] : gd[2 * e - 4], g2hi = e < 2 ? gc[2 * e + 1] : gd[2 * e - 3];
	v_and_b32_e32 v178, 0xffff0000, v44
	v_add_f32_e32 v24, v25, v24
	v_lshlrev_b32_e32 v175, 16, v44
	v_mul_f32_e32 v25, v178, v178
	v_fmac_f32_e32 v25, v175, v175
	v_and_b32_e32 v117, 0xffff0000, v45
	v_add_f32_e32 v24, v25, v24
	v_lshlrev_b32_e32 v118, 16, v45
	v_mul_f32_e32 v25, v117, v117
	v_fmac_f32_e32 v25, v118, v118
	v_and_b32_e32 v119, 0xffff0000, v46
	v_add_f32_e32 v24, v25, v24
	v_lshlrev_b32_e32 v120, 16, v46
	v_mul_f32_e32 v25, v119, v119
	v_fmac_f32_e32 v25, v120, v120
	v_and_b32_e32 v121, 0xffff0000, v47
	v_add_f32_e32 v24, v25, v24
	v_lshlrev_b32_e32 v122, 16, v47
	v_mul_f32_e32 v25, v121, v121
	v_fmac_f32_e32 v25, v122, v122
	v_and_b32_e32 v123, 0xffff0000, v48
	v_add_f32_e32 v24, v25, v24
	v_lshlrev_b32_e32 v124, 16, v48
	v_mul_f32_e32 v25, v123, v123
	v_fmac_f32_e32 v25, v124, v124
	v_and_b32_e32 v110, 0xffff0000, v49
	v_add_f32_e32 v24, v25, v24
	v_lshlrev_b32_e32 v111, 16, v49
	v_mul_f32_e32 v25, v110, v110
	v_fmac_f32_e32 v25, v111, v111
	v_and_b32_e32 v112, 0xffff0000, v50
	v_add_f32_e32 v24, v25, v24
	v_lshlrev_b32_e32 v113, 16, v50
	v_mul_f32_e32 v25, v112, v112
	v_fmac_f32_e32 v25, v113, v113
	v_and_b32_e32 v114, 0xffff0000, v51
	v_add_f32_e32 v24, v25, v24
	v_lshlrev_b32_e32 v115, 16, v51
	v_mul_f32_e32 v25, v114, v114
	v_fmac_f32_e32 v25, v115, v115
	v_and_b32_e32 v90, 0xffff0000, v52
	v_add_f32_e32 v24, v25, v24
	v_lshlrev_b32_e32 v116, 16, v52
	v_mul_f32_e32 v25, v90, v90
	v_fmac_f32_e32 v25, v116, v116
	v_and_b32_e32 v94, 0xffff0000, v53
	v_add_f32_e32 v24, v25, v24
	v_lshlrev_b32_e32 v98, 16, v53
	v_mul_f32_e32 v25, v94, v94
	v_fmac_f32_e32 v25, v98, v98
	v_and_b32_e32 v99, 0xffff0000, v54
	v_add_f32_e32 v24, v25, v24
	v_lshlrev_b32_e32 v103, 16, v54
	v_mul_f32_e32 v25, v99, v99
	v_fmac_f32_e32 v25, v103, v103
	v_and_b32_e32 v104, 0xffff0000, v55
	v_add_f32_e32 v24, v25, v24
	v_lshlrev_b32_e32 v106, 16, v55
	v_mul_f32_e32 v25, v104, v104
	v_fmac_f32_e32 v25, v106, v106
	v_and_b32_e32 v107, 0xffff0000, v56
	v_add_f32_e32 v24, v25, v24
	v_lshlrev_b32_e32 v108, 16, v56
	v_mul_f32_e32 v25, v107, v107
	v_fmac_f32_e32 v25, v108, v108
	v_and_b32_e32 v82, 0xffff0000, v57
	v_add_f32_e32 v24, v25, v24
	v_lshlrev_b32_e32 v109, 16, v57
	v_mul_f32_e32 v25, v82, v82
	v_fmac_f32_e32 v25, v109, v109
	v_and_b32_e32 v83, 0xffff0000, v58
	v_add_f32_e32 v24, v25, v24
	v_lshlrev_b32_e32 v84, 16, v58
	v_mul_f32_e32 v25, v83, v83
	v_fmac_f32_e32 v25, v84, v84
	v_and_b32_e32 v85, 0xffff0000, v59
	v_add_f32_e32 v24, v25, v24
	v_lshlrev_b32_e32 v86, 16, v59
	v_mul_f32_e32 v25, v85, v85
	v_fmac_f32_e32 v25, v86, v86
	v_and_b32_e32 v87, 0xffff0000, v60
	v_add_f32_e32 v24, v25, v24
	v_lshlrev_b32_e32 v88, 16, v60
	v_mul_f32_e32 v25, v87, v87
	v_fmac_f32_e32 v25, v88, v88
	v_and_b32_e32 v89, 0xffff0000, v61
	v_add_f32_e32 v24, v25, v24
	v_lshlrev_b32_e32 v91, 16, v61
	v_mul_f32_e32 v25, v89, v89
	v_fmac_f32_e32 v25, v91, v91
	v_and_b32_e32 v92, 0xffff0000, v62
	v_add_f32_e32 v24, v25, v24
	v_lshlrev_b32_e32 v95, 16, v62
	v_mul_f32_e32 v25, v92, v92
	v_fmac_f32_e32 v25, v95, v95
	v_and_b32_e32 v93, 0xffff0000, v63
	v_add_f32_e32 v24, v25, v24
	v_lshlrev_b32_e32 v100, 16, v63
	v_mul_f32_e32 v25, v93, v93
	v_fmac_f32_e32 v25, v100, v100
	v_and_b32_e32 v97, 0xffff0000, v64
	v_add_f32_e32 v24, v25, v24
	v_lshlrev_b32_e32 v101, 16, v64
	v_mul_f32_e32 v25, v97, v97
	v_fmac_f32_e32 v25, v101, v101
	v_and_b32_e32 v102, 0xffff0000, v65
	v_add_f32_e32 v24, v25, v24
	v_lshlrev_b32_e32 v105, 16, v65
	v_mul_f32_e32 v25, v102, v102
	v_fmac_f32_e32 v25, v105, v105
	v_and_b32_e32 v58, 32, v96
	v_add_u32_e32 v254, 0x1e800, v58
	v_add_f32_e32 v146, v25, v24
	ds_read_b128 v[24:27], v254 offset:16
	ds_read_b128 v[28:31], v254
	ds_read_b128 v[134:137], v254 offset:80
	ds_read_b128 v[138:141], v254 offset:64
	s_and_b32 s81, s0, 0x700
	v_add_u32_e32 v42, s81, v66
	v_ashrrev_i32_e32 v43, 31, v42
	v_lshlrev_b64 v[42:43], 7, v[42:43]
	v_lshl_add_u64 v[66:67], s[8:9], 0, v[42:43]
	v_and_b32_e32 v42, 0xffff0000, v75
	v_and_b32_e32 v46, 0xffff0000, v74
	v_lshlrev_b32_e32 v44, 16, v75
	v_lshlrev_b32_e32 v48, 16, v74
	v_mov_b32_e32 v52, v42
	v_mov_b32_e32 v53, v46
	v_mov_b32_e32 v50, v44
	v_mov_b32_e32 v51, v48
	v_pk_mul_f32 v[52:53], v[52:53], v[52:53]
	v_and_b32_e32 v54, 0xffff0000, v72
	v_pk_fma_f32 v[78:79], v[50:51], v[50:51], v[52:53]
	v_and_b32_e32 v50, 0xffff0000, v73
	v_lshlrev_b32_e32 v52, 16, v73
	v_lshlrev_b32_e32 v56, 16, v72
	v_mov_b32_e32 v62, v50
	v_mov_b32_e32 v63, v54
	v_mov_b32_e32 v60, v52
	v_mov_b32_e32 v61, v56
	v_pk_mul_f32 v[62:63], v[62:63], v[62:63]
	v_lshlrev_b32_e32 v53, 16, v69
	v_and_b32_e32 v51, 0xffff0000, v69
	v_lshlrev_b32_e32 v57, 16, v68
	v_and_b32_e32 v55, 0xffff0000, v68
	v_pk_fma_f32 v[68:69], v[60:61], v[60:61], v[62:63]
	v_and_b32_e32 v60, 0xffff0000, v23
	v_lshlrev_b32_e32 v64, 16, v22
	v_and_b32_e32 v22, 0xffff0000, v22
	v_lshlrev_b32_e32 v45, 16, v71
	v_and_b32_e32 v43, 0xffff0000, v71
	v_lshlrev_b32_e32 v49, 16, v70
	v_and_b32_e32 v47, 0xffff0000, v70
	v_lshlrev_b32_e32 v62, 16, v23
	v_mov_b32_e32 v70, v60
	v_mov_b32_e32 v71, v22
	v_lshlrev_b32_e32 v63, 16, v19
	v_and_b32_e32 v61, 0xffff0000, v19
	v_lshlrev_b32_e32 v65, 16, v18
	v_and_b32_e32 v23, 0xffff0000, v18
	v_mov_b32_e32 v18, v62
	v_mov_b32_e32 v19, v64
	v_pk_mul_f32 v[70:71], v[70:71], v[70:71]
	v_and_b32_e32 v75, 0xffff0000, v16
	v_and_b32_e32 v74, 0xffff0000, v20
	v_pk_fma_f32 v[128:129], v[18:19], v[18:19], v[70:71]
	v_lshlrev_b32_e32 v72, 16, v21
	v_and_b32_e32 v71, 0xffff0000, v17
	v_and_b32_e32 v70, 0xffff0000, v21
	v_lshlrev_b32_e32 v77, 16, v16
	v_lshlrev_b32_e32 v76, 16, v20
	v_pk_mul_f32 v[20:21], v[74:75], v[74:75]
	v_lshlrev_b32_e32 v73, 16, v17
; __device__ __forceinline__ float bflo(unsigned w) { return __uint_as_float(w << 16); }
; __device__ __forceinline__ float bfhi(unsigned w) { return __uint_as_float(w & 0xffff0000u); }
; __device__ __forceinline__ void attn_body(const u16* __restrict__ Qb, const u16* __restrict__ Kn, const u16* __restrict__ Kr,
;                                           u16* __restrict__ Ob, char* lds, int tid, const float* __restrict__ gq_, const float* __restrict__ tab_, int qpos0, float negM) {
;     ...
;     { auto rr = __builtin_amdgcn_permlane32_swap(__float_as_uint(ss), __float_as_uint(ss), false, false);
;       ss = __uint_as_float(rr[0]) + __uint_as_float(rr[1]); }
;     const float rq = rsqrtf(ss * (1.f / 192.f) + EPS) * QSCALE;
;     const float* gq = gq_ + hi * 8;
; #pragma unroll
;     for (int d0 = 0; d0 < 8; ++d0) {
;       const f32x4 g0 = *reinterpret_cast<const f32x4*>(gq + d0 * 16), g1 = *reinterpret_cast<const f32x4*>(gq + d0 * 16 + 4);
;       const u32x4 w = qw[d0];
;       const u32x4 o = {cvtpk(bflo(w[0]) * rq * g0[0], bfhi(w[0]) * rq * g0[1]), cvtpk(bflo(w[1]) * rq * g0[2], bfhi(w[1]) * rq * g0[3]),
;                        cvtpk(bflo(w[2]) * rq * g1[0], bfhi(w[2]) * rq * g1[1]), cvtpk(bflo(w[3]) * rq * g1[2], bfhi(w[3]) * rq * g1[3])};
;       qr[d0] = *reinterpret_cast<const bf16x8*>(&o); }
;     const float* tcp = tab_ + (size_t)(qpos0 + wid * 32 + r32) * 32 + hi * 8; const float* tsp = tcp + SEQ * 32;
; #pragma unroll
;     for (int dd = 0; dd < 2; ++dd) {
;       float x1[8], x2[8], c_[8], s_[8];
;       { const f32x4 ga = *reinterpret_cast<const f32x4*>(gq + 128 + dd * 16), gb = *reinterpret_cast<const f32x4*>(gq + 128 + dd * 16 + 4);
;         const f32x4 gc = *reinterpret_cast<const f32x4*>(gq + 160 + dd * 16), gd = *reinterpret_cast<const f32x4*>(gq + 160 + dd * 16 + 4);
;         const f32x4 ca = *reinterpret_cast<const f32x4*>(tcp + dd * 16), cb = *reinterpret_cast<const f32x4*>(tcp + dd * 16 + 4);
;         const f32x4 sa = *reinterpret_cast<const f32x4*>(tsp + dd * 16), sb = *reinterpret_cast<const f32x4*>(tsp + dd * 16 + 4);
	v_pk_mul_f32 v[18:19], v[70:71], v[70:71]
	v_pk_fma_f32 v[20:21], v[76:77], v[76:77], v[20:21]
	v_mul_f32_e32 v152, v65, v65
	v_pk_fma_f32 v[130:131], v[72:73], v[72:73], v[18:19]
	v_add_f32_e32 v21, v21, v146
	v_mul_f32_e32 v151, v63, v63
	v_fmac_f32_e32 v152, v23, v23
	v_add_f32_e32 v21, v131, v21
	v_mul_f32_e32 v150, v57, v57
	v_fmac_f32_e32 v151, v61, v61
	v_add_f32_e32 v21, v152, v21
	v_mul_f32_e32 v149, v53, v53
	v_fmac_f32_e32 v150, v55, v55
	v_add_f32_e32 v21, v151, v21
	v_mul_f32_e32 v148, v49, v49
	v_fmac_f32_e32 v149, v51, v51
	v_add_f32_e32 v21, v150, v21
	v_mul_f32_e32 v147, v45, v45
	v_fmac_f32_e32 v148, v47, v47
	v_add_f32_e32 v21, v149, v21
	v_fmac_f32_e32 v147, v43, v43
	v_add_f32_e32 v21, v148, v21
	v_add_f32_e32 v21, v147, v21
	v_add_f32_e32 v20, v20, v21
	v_add_f32_e32 v20, v130, v20
	v_add_f32_e32 v20, v129, v20
	v_add_f32_e32 v20, v128, v20
	v_add_f32_e32 v20, v69, v20
	v_add_f32_e32 v20, v68, v20
	v_add_f32_e32 v20, v79, v20
	v_add_f32_e32 v20, v78, v20
	v_mov_b32_e32 v21, v20
	s_nop 1
	v_permlane32_swap_b32_e32 v20, v21
	ds_read_b128 v[16:19], v254 offset:144
	ds_read_b128 v[142:145], v254 offset:128
	v_add_f32_e32 v20, v20, v21
	v_mov_b32_e32 v21, 0x358637bd
	v_fmamk_f32 v20, v20, 0x3baaaaab, v21
	v_mul_f32_e32 v21, 0x4b800000, v20
	v_cmp_gt_f32_e32 vcc, s77, v20
	ds_read_b128 v[146:149], v254 offset:208
	ds_read_b128 v[150:153], v254 offset:192
	v_cndmask_b32_e32 v20, v20, v21, vcc
	v_rsq_f32_e32 v20, v20
	v_mov_b32_e32 v59, v177
	v_lshl_add_u64 v[68:69], v[66:67], 0, v[58:59]
	v_lshl_add_u64 v[78:79], v[68:69], 0, s[10:11]
	global_load_dwordx4 v[212:215], v[78:79], off
	global_load_dwordx4 v[216:219], v[68:69], off offset:16
	global_load_dwordx4 v[220:223], v[68:69], off
	global_load_dwordx4 v[224:227], v[78:79], off offset:16
	global_load_dwordx4 v[228:231], v[78:79], off offset:64
	global_load_dwordx4 v[232:235], v[68:69], off offset:80
	global_load_dwordx4 v[236:239], v[68:69], off offset:64
	global_load_dwordx4 v[240:243], v[78:79], off offset:80
	v_mul_f32_e32 v21, 0x45800000, v20
	v_cndmask_b32_e32 v20, v20, v21, vcc
	v_mul_f32_e32 v20, 0x3dd53b94, v20
	v_mul_f32_e32 v21, v20, v132
	s_waitcnt vmcnt(0) lgkmcnt(0)
	v_mul_f32_e32 v21, v28, v21
	v_mul_f32_e32 v28, v20, v133
	v_mul_f32_e32 v28, v29, v28
	s_nop 0
	v_cvt_pk_bf16_f32 v128, v21, v28
	v_mul_f32_e32 v21, v20, v154
	v_mul_f32_e32 v21, v30, v21
	v_mul_f32_e32 v28, v20, v155
	v_mul_f32_e32 v28, v31, v28
	s_nop 0
	v_cvt_pk_bf16_f32 v129, v21, v28
	v_mul_f32_e32 v21, v20, v162
	ds_read_b128 v[154:157], v254 offset:272
	ds_read_b128 v[158:161], v254 offset:256
	v_mul_f32_e32 v21, v24, v21
	v_mul_f32_e32 v24, v20, v163
	v_mul_f32_e32 v24, v25, v24
	s_nop 0
	v_cvt_pk_bf16_f32 v130, v21, v24
	v_mul_f32_e32 v24, v20, v165
	v_mul_f32_e32 v21, v20, v164
	v_mul_f32_e32 v24, v27, v24
	v_mul_f32_e32 v21, v26, v21
	s_nop 0
	v_cvt_pk_bf16_f32 v131, v21, v24
	v_mul_f32_e32 v24, v20, v167
	v_mul_f32_e32 v21, v20, v166
	v_mul_f32_e32 v24, v139, v24
	v_mul_f32_e32 v21, v138, v21
	s_nop 0
	v_cvt_pk_bf16_f32 v132, v21, v24
	v_mul_f32_e32 v24, v20, v169
	v_mul_f32_e32 v21, v20, v168
	v_mul_f32_e32 v24, v141, v24
	v_mul_f32_e32 v21, v140, v21
	s_nop 0
	v_cvt_pk_bf16_f32 v133, v21, v24
	ds_read_b128 v[24:27], v254 offset:336
	ds_read_b128 v[28:31], v254 offset:320
	v_mul_f32_e32 v21, v20, v126
	v_mul_f32_e32 v21, v134, v21
	v_mul_f32_e32 v59, v20, v125
	v_mul_f32_e32 v59, v135, v59
	s_nop 0
	v_cvt_pk_bf16_f32 v134, v21, v59
	v_mul_f32_e32 v21, v20, v170
	v_mul_f32_e32 v21, v136, v21
	v_mul_f32_e32 v59, v20, v127
	v_mul_f32_e32 v59, v137, v59
	s_nop 0
	v_cvt_pk_bf16_f32 v135, v21, v59
	v_mul_f32_e32 v21, v20, v171
	v_mul_f32_e32 v59, v20, v172
	ds_read_b128 v[162:165], v254 offset:400
	ds_read_b128 v[166:169], v254 offset:384
	v_lshl_add_u64 v[66:67], v[68:69], 0, s[12:13]
	v_and_b32_e32 v209, 63, v96
	v_and_b32_e32 v206, 31, v96
	v_mov_b32_e32 v33, v177
	s_mov_b32 s50, 0
	v_mul_f32_e32 v21, v21, v142
	v_mul_f32_e32 v59, v59, v143
	s_nop 0
	v_cvt_pk_bf16_f32 v136, v21, v59
	v_mul_f32_e32 v21, v20, v173
	v_mul_f32_e32 v21, v21, v144
	v_mul_f32_e32 v59, v20, v174
	v_mul_f32_e32 v59, v59, v145
	s_nop 0
	v_cvt_pk_bf16_f32 v137, v21, v59
	v_mul_f32_e32 v21, v20, v175
	v_mul_f32_e32 v16, v21, v16
	v_mul_f32_e32 v21, v20, v178
	v_mul_f32_e32 v17, v21, v17
	s_nop 0
	v_cvt_pk_bf16_f32 v138, v16, v17
	v_mul_f32_e32 v16, v20, v118
	v_mul_f32_e32 v16, v16, v18
	v_mul_f32_e32 v17, v20, v117
	v_mul_f32_e32 v17, v17, v19
	s_nop 0
	v_cvt_pk_bf16_f32 v139, v16, v17
	v_mul_f32_e32 v16, v20, v120
	v_mul_f32_e32 v16, v16, v150
	v_mul_f32_e32 v17, v20, v119
	v_mul_f32_e32 v17, v17, v151
	s_nop 0
	v_cvt_pk_bf16_f32 v140, v16, v17
	v_mul_f32_e32 v16, v20, v122
	v_mul_f32_e32 v16, v16, v152
	v_mul_f32_e32 v17, v20, v121
	v_mul_f32_e32 v17, v17, v153
	s_nop 0
	v_cvt_pk_bf16_f32 v141, v16, v17
	v_mul_f32_e32 v16, v20, v124
	v_mul_f32_e32 v16, v16, v146
	v_mul_f32_e32 v17, v20, v123
	v_mul_f32_e32 v17, v17, v147
	s_nop 0
	v_cvt_pk_bf16_f32 v142, v16, v17
	v_mul_f32_e32 v16, v20, v111
	v_mul_f32_e32 v16, v16, v148
	v_mul_f32_e32 v17, v20, v110
	v_mul_f32_e32 v17, v17, v149
	s_nop 0
	v_cvt_pk_bf16_f32 v143, v16, v17
	v_mul_f32_e32 v16, v20, v113
	s_waitcnt vmcnt(0) lgkmcnt(0)
; __device__ __forceinline__ void attn_body(const u16* __restrict__ Qb, const u16* __restrict__ Kn, const u16* __restrict__ Kr,
;                                           u16* __restrict__ Ob, char* lds, int tid, const float* __restrict__ gq_, const float* __restrict__ tab_, int qpos0, float negM) {
;     ...
;     for (int d0 = 0; d0 < 8; ++d0) {
;       const f32x4 g0 = *reinterpret_cast<const f32x4*>(gq + d0 * 16), g1 = *reinterpret_cast<const f32x4*>(gq + d0 * 16 + 4);
;       const u32x4 w = qw[d0];
;       const u32x4 o = {cvtpk(bflo(w[0]) * rq * g0[0], bfhi(w[0]) * rq * g0[1]), cvtpk(bflo(w[1]) * rq * g0[2], bfhi(w[1]) * rq * g0[3]),
;                        cvtpk(bflo(w[2]) * rq * g1[0], bfhi(w[2]) * rq * g1[1]), cvtpk(bflo(w[3]) * rq * g1[2], bfhi(w[3]) * rq * g1[3])};
;       qr[d0] = *reinterpret_cast<const bf16x8*>(&o); }
;     const float* tcp = tab_ + (size_t)(qpos0 + wid * 32 + r32) * 32 + hi * 8; const float* tsp = tcp + SEQ * 32;
; #pragma unroll
;     for (int dd = 0; dd < 2; ++dd) {
;       float x1[8], x2[8], c_[8], s_[8];
;       { const f32x4 ga = *reinterpret_cast<const f32x4*>(gq + 128 + dd * 16), gb = *reinterpret_cast<const f32x4*>(gq + 128 + dd * 16 + 4);
;         const f32x4 gc = *reinterpret_cast<const f32x4*>(gq + 160 + dd * 16), gd = *reinterpret_cast<const f32x4*>(gq + 160 + dd * 16 + 4);
;         const f32x4 ca = *reinterpret_cast<const f32x4*>(tcp + dd * 16), cb = *reinterpret_cast<const f32x4*>(tcp + dd * 16 + 4);
;         const f32x4 sa = *reinterpret_cast<const f32x4*>(tsp + dd * 16), sb = *reinterpret_cast<const f32x4*>(tsp + dd * 16 + 4);
;         const u32x4 w1 = qw[8 + dd], w2 = qw[10 + dd];
; #pragma unroll
;         for (int e = 0; e < 4; ++e) {
;           const float g1lo = e < 2 ? ga[2 * e] : gb[2 * e - 4], g1hi = e < 2 ? ga[2 * e + 1] : gb[2 * e - 3];
;           const float g2lo = e < 2 ? gc[2 * e] : gd[2 * e - 4], g2hi = e < 2 ? gc[2 * e + 1] : gd[2 * e - 3];
;           x1[2 * e] = bflo(w1[e]) * rq * g1lo; x1[2 * e + 1] = bfhi(w1[e]) * rq * g1hi;
;           x2[2 * e] = bflo(w2[e]) * rq * g2lo; x2[2 * e + 1] = bfhi(w2[e]) * rq * g2hi;
;           c_[2 * e] = e < 2 ? ca[2 * e] : cb[2 * e - 4]; c_[2 * e + 1] = e < 2 ? ca[2 * e + 1] : cb[2 * e - 3];
;           s_[2 * e] = e < 2 ? sa[2 * e] : sb[2 * e - 4]; s_[2 * e + 1] = e < 2 ? sa[2 * e + 1] : sb[2 * e - 3]; } }
;       float y1[8], y2[8];
; #pragma unroll
	v_mul_f32_e32 v16, v16, v158
	v_mul_f32_e32 v17, v20, v112
	v_mul_f32_e32 v17, v17, v159
	s_nop 0
	v_cvt_pk_bf16_f32 v144, v16, v17
	v_mul_f32_e32 v16, v20, v115
	v_mul_f32_e32 v16, v16, v160
	v_mul_f32_e32 v17, v20, v114
	ds_read_b128 v[118:121], v254 offset:464
	ds_read_b128 v[122:125], v254 offset:448
	v_mul_f32_e32 v17, v17, v161
	s_nop 0
	v_cvt_pk_bf16_f32 v145, v16, v17
	v_mul_f32_e32 v16, v20, v116
	v_mul_f32_e32 v16, v16, v154
	v_mul_f32_e32 v17, v20, v90
	v_mul_f32_e32 v17, v17, v155
	s_nop 0
	v_cvt_pk_bf16_f32 v146, v16, v17
	v_mul_f32_e32 v16, v20, v98
	v_mul_f32_e32 v16, v16, v156
	v_mul_f32_e32 v17, v20, v94
	v_mul_f32_e32 v17, v17, v157
	s_nop 0
	v_cvt_pk_bf16_f32 v147, v16, v17
	v_mul_f32_e32 v16, v20, v103
	v_mul_f32_e32 v16, v16, v28
	v_mul_f32_e32 v17, v20, v99
	v_mul_f32_e32 v17, v17, v29
	s_nop 0
	v_cvt_pk_bf16_f32 v148, v16, v17
	v_mul_f32_e32 v16, v20, v106
	ds_read_b128 v[110:113], v254 offset:656
	ds_read_b128 v[114:117], v254 offset:640
	ds_read_b128 v[170:173], v254 offset:528
	ds_read_b128 v[178:181], v254 offset:512
	v_mul_f32_e32 v16, v16, v30
	v_mul_f32_e32 v17, v20, v104
	v_mul_f32_e32 v17, v17, v31
	s_nop 0
	v_cvt_pk_bf16_f32 v149, v16, v17
	v_mul_f32_e32 v16, v20, v108
	v_mul_f32_e32 v16, v16, v24
	v_mul_f32_e32 v17, v20, v107
	v_add_co_u32_e32 v98, vcc, s78, v68
	v_mul_f32_e32 v17, v17, v25
	s_nop 0
	v_cvt_pk_bf16_f32 v150, v16, v17
	v_mul_f32_e32 v16, v20, v109
	v_addc_co_u32_e32 v99, vcc, 0, v69, vcc
	v_mul_f32_e32 v21, v16, v26
	v_mov_b32_e32 v28, v212
	v_mov_b32_e32 v29, v213
	v_mov_b32_e32 v30, v214
	v_mov_b32_e32 v31, v215
	v_mov_b32_e32 v16, v216
	v_mov_b32_e32 v17, v217
	v_mov_b32_e32 v18, v218
	v_mov_b32_e32 v19, v219
	v_mov_b32_e32 v106, v220
	v_mov_b32_e32 v107, v221
	v_mov_b32_e32 v108, v222
	v_mov_b32_e32 v109, v223
	v_mul_f32_e32 v24, v20, v82
	v_mul_f32_e32 v24, v24, v27
	s_nop 0
	v_cvt_pk_bf16_f32 v151, v21, v24
	v_mul_f32_e32 v21, v20, v84
	v_mul_f32_e32 v21, v21, v166
	v_mul_f32_e32 v24, v20, v83
	v_mul_f32_e32 v24, v24, v167
	s_nop 0
	v_cvt_pk_bf16_f32 v152, v21, v24
	v_mul_f32_e32 v21, v20, v86
	v_mul_f32_e32 v21, v21, v168
	v_mul_f32_e32 v24, v20, v85
	v_mul_f32_e32 v24, v24, v169
	s_nop 0
	v_cvt_pk_bf16_f32 v153, v21, v24
	v_mul_f32_e32 v21, v20, v88
	v_mul_f32_e32 v21, v21, v162
	v_mul_f32_e32 v24, v20, v87
	v_mul_f32_e32 v24, v24, v163
	s_nop 0
	v_cvt_pk_bf16_f32 v154, v21, v24
	v_mul_f32_e32 v21, v20, v91
	v_mul_f32_e32 v21, v21, v164
	v_mul_f32_e32 v24, v20, v89
	v_mul_f32_e32 v24, v24, v165
	s_nop 0
	v_cvt_pk_bf16_f32 v155, v21, v24
	v_mul_f32_e32 v21, v20, v95
	v_mul_f32_e32 v24, v20, v92
	v_mul_f32_e32 v59, v20, v93
	s_waitcnt vmcnt(0) lgkmcnt(0)
	v_mul_f32_e32 v21, v21, v122
	v_mul_f32_e32 v24, v24, v123
	s_nop 0
	v_cvt_pk_bf16_f32 v156, v21, v24
	v_mul_f32_e32 v21, v20, v100
	v_mul_f32_e32 v21, v21, v124
	v_mov_b32_e32 v24, v224
	v_mov_b32_e32 v25, v225
	v_mov_b32_e32 v26, v226
	v_mov_b32_e32 v27, v227
	v_mul_f32_e32 v59, v59, v125
	s_nop 0
	v_cvt_pk_bf16_f32 v157, v21, v59
	v_mul_f32_e32 v21, v20, v101
	v_mul_f32_e32 v21, v21, v118
	v_mul_f32_e32 v59, v20, v97
	v_mul_f32_e32 v59, v59, v119
	s_nop 0
	v_cvt_pk_bf16_f32 v158, v21, v59
	v_mul_f32_e32 v21, v20, v105
	v_mul_f32_e32 v21, v21, v120
	v_pk_mul_f32 v[74:75], v[20:21], v[74:75] op_sel_hi:[0,1]
	v_mul_f32_e32 v59, v20, v102
	v_pk_mul_f32 v[70:71], v[20:21], v[70:71] op_sel_hi:[0,1]
	v_mul_f32_e32 v59, v59, v121
	v_mov_b32_e32 v79, v178
	v_mov_b32_e32 v178, v115
	v_pk_mul_f32 v[90:91], v[74:75], v[178:179]
	v_mov_b32_e32 v75, v180
	v_mov_b32_e32 v180, v117
	v_pk_mul_f32 v[76:77], v[20:21], v[76:77] op_sel_hi:[0,1]
	v_mov_b32_e32 v78, v114
	v_pk_mul_f32 v[72:73], v[20:21], v[72:73] op_sel_hi:[0,1]
	v_mov_b32_e32 v74, v116
	v_pk_mul_f32 v[100:101], v[70:71], v[180:181]
	v_pk_mul_f32 v[64:65], v[20:21], v[64:65] op_sel_hi:[0,1]
	v_mov_b32_e32 v70, v110
	v_mov_b32_e32 v71, v170
	s_nop 0
	v_cvt_pk_bf16_f32 v159, v21, v59
	v_pk_mul_f32 v[78:79], v[76:77], v[78:79]
	v_pk_mul_f32 v[94:95], v[72:73], v[74:75]
	v_pk_mul_f32 v[102:103], v[64:65], v[70:71]
	ds_read_b128 v[70:73], v254 offset:720
	ds_read_b128 v[74:77], v254 offset:704
	ds_read_b128 v[82:85], v254 offset:592
	ds_read_b128 v[86:89], v254 offset:576
	v_pk_mul_f32 v[58:59], v[20:21], v[62:63] op_sel_hi:[0,1]
	v_mov_b32_e32 v62, v112
	v_mov_b32_e32 v63, v172
	v_pk_mul_f32 v[104:105], v[58:59], v[62:63]
	v_mov_b32_e32 v62, v28
	v_mov_b32_e32 v63, v106
	v_pk_mul_f32 v[62:63], v[78:79], v[62:63]
	v_pk_mul_f32 v[22:23], v[20:21], v[22:23] op_sel_hi:[0,1]
	v_pk_mul_f32 v[58:59], v[20:21], v[60:61] op_sel_hi:[0,1]
	v_sub_f32_e32 v21, v63, v62
	v_mov_b32_e32 v62, v106
	v_mov_b32_e32 v63, v28
	v_pk_mul_f32 v[62:63], v[78:79], v[62:63]
	v_mov_b32_e32 v106, v29
	v_mov_b32_e32 v172, v113
	v_add_f32_e32 v78, v62, v63
	v_pk_mul_f32 v[62:63], v[90:91], v[106:107]
	v_mov_b32_e32 v28, v107
	v_mov_b32_e32 v170, v111
	v_pk_mul_f32 v[110:111], v[58:59], v[172:173]
	v_mov_b32_e32 v58, v228
	v_mov_b32_e32 v59, v229
	v_mov_b32_e32 v60, v230
	v_mov_b32_e32 v61, v231
	v_sub_f32_e32 v79, v63, v62
	v_pk_mul_f32 v[28:29], v[90:91], v[28:29]
	v_mov_b32_e32 v62, v232
	v_mov_b32_e32 v63, v233
	v_mov_b32_e32 v64, v234
	v_mov_b32_e32 v65, v235
	v_mov_b32_e32 v90, v236
	v_mov_b32_e32 v91, v237
	v_mov_b32_e32 v92, v238
	v_mov_b32_e32 v93, v239
	v_add_f32_e32 v97, v28, v29
	v_mov_b32_e32 v28, v30
	v_mov_b32_e32 v29, v108
	v_pk_mul_f32 v[28:29], v[94:95], v[28:29]
	v_pk_mul_f32 v[22:23], v[22:23], v[170:171]
	v_sub_f32_e32 v68, v29, v28
	v_mov_b32_e32 v28, v108
	v_mov_b32_e32 v29, v30
	v_pk_mul_f32 v[28:29], v[94:95], v[28:29]
	v_mov_b32_e32 v108, v31
	v_add_f32_e32 v69, v28, v29
	v_pk_mul_f32 v[28:29], v[100:101], v[108:109]
	v_mov_b32_e32 v30, v109
	v_sub_f32_e32 v94, v29, v28
	v_pk_mul_f32 v[28:29], v[100:101], v[30:31]
	s_nop 0
	v_cvt_pk_bf16_f32 v164, v21, v79
	v_pk_mul_f32 v[46:47], v[20:21], v[46:47] op_sel_hi:[0,1]
	v_add_f32_e32 v95, v28, v29
	v_mov_b32_e32 v28, v240
	v_mov_b32_e32 v29, v241
	v_mov_b32_e32 v30, v242
	v_mov_b32_e32 v31, v243
	v_mov_b32_e32 v67, v16
	v_pk_mul_f32 v[44:45], v[20:21], v[44:45] op_sel_hi:[0,1]
	s_waitcnt vmcnt(0) lgkmcnt(0)
	s_nop 0
	v_cvt_pk_bf16_f32 v165, v68, v94
	s_nop 0
	v_cvt_pk_bf16_f32 v160, v78, v97
	s_waitcnt vmcnt(0) lgkmcnt(0)
	v_mov_b32_e32 v66, v24
	v_pk_mul_f32 v[66:67], v[102:103], v[66:67]
	s_nop 0
	v_cvt_pk_bf16_f32 v161, v69, v95
	s_barrier
; __device__ __forceinline__ void attn_body(const u16* __restrict__ Qb, const u16* __restrict__ Kn, const u16* __restrict__ Kr,
;                                           u16* __restrict__ Ob, char* lds, int tid, const float* __restrict__ gq_, const float* __restrict__ tab_, int qpos0, float negM) {
;     ...
;       float x1[8], x2[8], c_[8], s_[8];
;       { const f32x4 ga = *reinterpret_cast<const f32x4*>(gq + 128 + dd * 16), gb = *reinterpret_cast<const f32x4*>(gq + 128 + dd * 16 + 4);
;         const f32x4 gc = *reinterpret_cast<const f32x4*>(gq + 160 + dd * 16), gd = *reinterpret_cast<const f32x4*>(gq + 160 + dd * 16 + 4);
;         const f32x4 ca = *reinterpret_cast<const f32x4*>(tcp + dd * 16), cb = *reinterpret_cast<const f32x4*>(tcp + dd * 16 + 4);
;         const f32x4 sa = *reinterpret_cast<const f32x4*>(tsp + dd * 16), sb = *reinterpret_cast<const f32x4*>(tsp + dd * 16 + 4);
;         const u32x4 w1 = qw[8 + dd], w2 = qw[10 + dd];
; #pragma unroll
;         for (int e = 0; e < 4; ++e) {
;           const float g1lo = e < 2 ? ga[2 * e] : gb[2 * e - 4], g1hi = e < 2 ? ga[2 * e + 1] : gb[2 * e - 3];
;           const float g2lo = e < 2 ? gc[2 * e] : gd[2 * e - 4], g2hi = e < 2 ? gc[2 * e + 1] : gd[2 * e - 3];
;           x1[2 * e] = bflo(w1[e]) * rq * g1lo; x1[2 * e + 1] = bfhi(w1[e]) * rq * g1hi;
;           x2[2 * e] = bflo(w2[e]) * rq * g2lo; x2[2 * e + 1] = bfhi(w2[e]) * rq * g2hi;
;           c_[2 * e] = e < 2 ? ca[2 * e] : cb[2 * e - 4]; c_[2 * e + 1] = e < 2 ? ca[2 * e + 1] : cb[2 * e - 3];
;           s_[2 * e] = e < 2 ? sa[2 * e] : sb[2 * e - 4]; s_[2 * e + 1] = e < 2 ? sa[2 * e + 1] : sb[2 * e - 3]; } }
;       float y1[8], y2[8];
; #pragma unroll
;       for (int e = 0; e < 8; ++e) { y1[e] = x1[e] * c_[e] - x2[e] * s_[e]; y2[e] = x2[e] * c_[e] + x1[e] * s_[e]; }
;       const u32x4 o1 = {cvtpk(y1[0], y1[1]), cvtpk(y1[2], y1[3]), cvtpk(y1[4], y1[5]), cvtpk(y1[6], y1[7])};
;       const u32x4 o2 = {cvtpk(y2[0], y2[1]), cvtpk(y2[2], y2[3]), cvtpk(y2[4], y2[5]), cvtpk(y2[6], y2[7])};
;       qr[8 + dd] = *reinterpret_cast<const bf16x8*>(&o1); qr[10 + dd] = *reinterpret_cast<const bf16x8*>(&o2); }
;   }
;   const int vrb = (int)(uintptr_t)lds + v_rd_base(lane);
;   f32x16 pA0, pA1, pB0, pB1; bf16x8 pa0, pa1, pa2, pa3; constexpr int NT = SEQ / KVBLK;
;   WAITV(0); TBAR();
;   AISSUE(KVBLK, STG);
	v_sub_f32_e32 v98, v67, v66
	v_mov_b32_e32 v66, v16
	v_mov_b32_e32 v67, v24
	v_pk_mul_f32 v[66:67], v[102:103], v[66:67]
	v_mov_b32_e32 v16, v25
	v_mov_b32_e32 v24, v17
	v_add_f32_e32 v99, v66, v67
	v_pk_mul_f32 v[66:67], v[22:23], v[16:17]
	v_pk_mul_f32 v[16:17], v[22:23], v[24:25]
	v_sub_f32_e32 v66, v67, v66
	v_add_f32_e32 v22, v16, v17
	v_mov_b32_e32 v16, v26
	v_mov_b32_e32 v17, v18
	v_pk_mul_f32 v[16:17], v[104:105], v[16:17]
	s_nop 0
	v_cvt_pk_bf16_f32 v162, v99, v22
	s_nop 0
	v_cvt_pk_bf16_f32 v166, v98, v66
	v_mov_b32_e32 v25, v88
	v_sub_f32_e32 v23, v17, v16
	v_mov_b32_e32 v16, v18
	v_mov_b32_e32 v17, v26
	v_pk_mul_f32 v[16:17], v[104:105], v[16:17]
	v_mov_b32_e32 v18, v27
	v_add_f32_e32 v24, v16, v17
	v_pk_mul_f32 v[16:17], v[110:111], v[18:19]
	v_mov_b32_e32 v26, v19
	v_sub_f32_e32 v18, v17, v16
	v_pk_mul_f32 v[16:17], v[110:111], v[26:27]
	s_nop 0
	v_cvt_pk_bf16_f32 v167, v23, v18
	v_mov_b32_e32 v18, v74
	v_add_f32_e32 v16, v16, v17
	s_nop 0
	v_cvt_pk_bf16_f32 v163, v24, v16
	v_pk_mul_f32 v[16:17], v[20:21], v[56:57] op_sel_hi:[0,1]
	v_mov_b32_e32 v19, v86
	v_pk_mul_f32 v[22:23], v[20:21], v[52:53] op_sel_hi:[0,1]
	v_mov_b32_e32 v24, v76
	v_pk_mul_f32 v[16:17], v[16:17], v[18:19]
	v_pk_mul_f32 v[18:19], v[20:21], v[54:55] op_sel_hi:[0,1]
	v_pk_mul_f32 v[22:23], v[22:23], v[24:25]
	v_pk_mul_f32 v[24:25], v[20:21], v[50:51] op_sel_hi:[0,1]
	v_pk_mul_f32 v[26:27], v[20:21], v[48:49] op_sel_hi:[0,1]
	v_mov_b32_e32 v48, v70
	v_mov_b32_e32 v49, v82
	v_pk_mul_f32 v[20:21], v[20:21], v[42:43] op_sel_hi:[0,1]
	v_mov_b32_e32 v42, v58
	v_mov_b32_e32 v43, v90
	v_pk_mul_f32 v[26:27], v[26:27], v[48:49]
	v_mov_b32_e32 v48, v72
	v_mov_b32_e32 v49, v84
	v_pk_mul_f32 v[42:43], v[16:17], v[42:43]
	v_mov_b32_e32 v86, v75
	v_pk_mul_f32 v[44:45], v[44:45], v[48:49]
	v_sub_f32_e32 v48, v43, v42
	v_mov_b32_e32 v42, v90
	v_mov_b32_e32 v43, v58
	v_pk_mul_f32 v[18:19], v[18:19], v[86:87]
	v_pk_mul_f32 v[16:17], v[16:17], v[42:43]
	v_mov_b32_e32 v90, v59
	v_add_f32_e32 v42, v16, v17
	v_pk_mul_f32 v[16:17], v[18:19], v[90:91]
	v_mov_b32_e32 v58, v91
	v_sub_f32_e32 v43, v17, v16
	v_pk_mul_f32 v[16:17], v[18:19], v[58:59]
	v_mov_b32_e32 v88, v77
	v_add_f32_e32 v18, v16, v17
	v_mov_b32_e32 v16, v60
	v_mov_b32_e32 v17, v92
	v_pk_mul_f32 v[16:17], v[22:23], v[16:17]
	v_pk_mul_f32 v[24:25], v[24:25], v[88:89]
	v_sub_f32_e32 v19, v17, v16
	v_mov_b32_e32 v16, v92
	v_mov_b32_e32 v17, v60
	v_pk_mul_f32 v[16:17], v[22:23], v[16:17]
	v_mov_b32_e32 v92, v61
	v_add_f32_e32 v22, v16, v17
	v_pk_mul_f32 v[16:17], v[24:25], v[92:93]
	v_mov_b32_e32 v60, v93
	v_sub_f32_e32 v23, v17, v16
	v_pk_mul_f32 v[16:17], v[24:25], v[60:61]
	v_mov_b32_e32 v82, v71
	v_add_f32_e32 v24, v16, v17
	v_mov_b32_e32 v16, v28
	v_mov_b32_e32 v17, v62
	v_pk_mul_f32 v[16:17], v[26:27], v[16:17]
	v_pk_mul_f32 v[46:47], v[46:47], v[82:83]
	v_sub_f32_e32 v25, v17, v16
	v_mov_b32_e32 v16, v62
	v_mov_b32_e32 v17, v28
	v_pk_mul_f32 v[16:17], v[26:27], v[16:17]
	v_mov_b32_e32 v62, v29
	v_add_f32_e32 v26, v16, v17
	v_pk_mul_f32 v[16:17], v[46:47], v[62:63]
	v_mov_b32_e32 v28, v63
	v_sub_f32_e32 v27, v17, v16
	v_pk_mul_f32 v[16:17], v[46:47], v[28:29]
	v_mov_b32_e32 v84, v73
	v_add_f32_e32 v28, v16, v17
	v_mov_b32_e32 v16, v30
	v_mov_b32_e32 v17, v64
	v_pk_mul_f32 v[16:17], v[44:45], v[16:17]
	v_pk_mul_f32 v[20:21], v[20:21], v[84:85]
	v_sub_f32_e32 v29, v17, v16
	v_mov_b32_e32 v16, v64
	v_mov_b32_e32 v17, v30
	v_pk_mul_f32 v[16:17], v[44:45], v[16:17]
	v_mov_b32_e32 v64, v31
	v_add_f32_e32 v44, v16, v17
	v_pk_mul_f32 v[16:17], v[20:21], v[64:65]
	v_mov_b32_e32 v30, v65
	v_sub_f32_e32 v45, v17, v16
	v_pk_mul_f32 v[16:17], v[20:21], v[30:31]
	s_nop 0
	v_cvt_pk_bf16_f32 v168, v42, v18
	v_lshlrev_b32_e32 v18, 1, v96
	v_add_f32_e32 v16, v16, v17
	v_lshlrev_b32_e32 v17, 4, v96
	s_nop 0
	v_cvt_pk_bf16_f32 v171, v44, v16
	v_lshlrev_b32_e32 v16, 3, v209
	v_and_b32_e32 v17, 0xc0, v17
	v_and_or_b32 v17, v16, 24, v17
	v_and_b32_e32 v18, 32, v18
	v_and_b32_e32 v16, 0x100, v16
	v_or3_b32 v212, v17, v18, v16
	s_nop 0
	v_cvt_pk_bf16_f32 v172, v48, v43
	s_nop 0
	v_cvt_pk_bf16_f32 v173, v19, v23
	s_nop 0
	v_cvt_pk_bf16_f32 v174, v25, v27
	s_nop 0
	v_cvt_pk_bf16_f32 v175, v29, v45
	s_nop 0
	v_cvt_pk_bf16_f32 v169, v22, v24
	s_nop 0
	v_cvt_pk_bf16_f32 v170, v26, v28
	v_add_u32_e32 v16, 0xe000, v211
	s_add_u32 s48, s48, 0x40000
	v_readfirstlane_b32 s51, v16
	v_add_u32_e32 v16, 0x10000, v211
	s_addc_u32 s49, s49, 0
	s_mov_b32 m0, s51
	v_readfirstlane_b32 s51, v16
	v_add_u32_e32 v19, 0x12000, v211
	global_load_lds_dwordx4 v176, s[48:49]
	s_mov_b32 m0, s51
	v_readfirstlane_b32 s51, v19
	v_add_u32_e32 v18, 0xa000, v211
	global_load_lds_dwordx4 v32, s[48:49]
	v_lshl_add_u64 v[16:17], v[40:41], 0, s[14:15]
	s_mov_b32 m0, s51
	v_readfirstlane_b32 s51, v18
	global_load_lds_dwordx4 v[16:17], off
	v_add_u32_e32 v16, 0xc000, v211
	s_mov_b32 m0, s51
	v_readfirstlane_b32 s51, v16
	global_load_lds_dwordx4 v80, s[48:49]
	s_mov_b32 m0, s51
	s_nop 0
	global_load_lds_dwordx4 v81, s[48:49]
	s_setprio 1
	v_bitop3_b32 v16, v207, v96, 15 bitop3:0x78
	v_lshlrev_b32_e32 v213, 8, v206
	v_lshlrev_b32_e32 v214, 4, v16
	v_or_b32_e32 v16, v213, v214
	ds_read_b128 v[40:43], v16 offset:16384
	ds_read_b128 v[44:47], v16 offset:24576
	v_and_b32_e32 v48, 15, v96
	v_lshlrev_b32_e32 v222, 7, v206
	s_waitcnt lgkmcnt(0)
	v_mfma_f32_32x32x16_bf16 v[16:31], v[40:43], v[128:131], v[0:15]
	v_bitop3_b32 v40, v207, v48, 2 bitop3:0x36
	v_lshlrev_b32_e32 v215, 4, v40
	v_mfma_f32_32x32x16_bf16 v[80:95], v[44:47], v[128:131], v[0:15]
	v_or_b32_e32 v44, v213, v215
	ds_read_b128 v[40:43], v44 offset:16384
	ds_read_b128 v[44:47], v44 offset:24576
	s_waitcnt lgkmcnt(0)
; __device__ __forceinline__ void qkt(f32x16& p0, f32x16& p1, const char* Ks, const bf16x8* qr, int r32, int hi, float negM) {
; #pragma unroll
;   for (int r = 0; r < 16; ++r) { p0[r] = negM; p1[r] = negM; }
;   __builtin_amdgcn_s_setprio(1);
;   const char* kn = Ks + r32 * 256; const int xn = r32 & 15;
; #pragma unroll
;   for (int d0 = 0; d0 < 8; ++d0) { const int off = ((d0 * 2 + hi) ^ xn) << 4;
;     bf16x8 b0 = *reinterpret_cast<const bf16x8*>(kn + off);
;     bf16x8 b1 = *reinterpret_cast<const bf16x8*>(kn + 32 * 256 + off);
;     p0 = __builtin_amdgcn_mfma_f32_32x32x16_bf16(b0, qr[d0], p0, 0, 0, 0);
;     p1 = __builtin_amdgcn_mfma_f32_32x32x16_bf16(b1, qr[d0], p1, 0, 0, 0); }
;   const char* kr = Ks + KROPE_OFF + r32 * 128; const int xr = (r32 >> 1) & 7;
; #pragma unroll
;   for (int d0 = 8; d0 < 12; ++d0) { const int off = (((d0 - 8) * 2 + hi) ^ xr) << 4;
;     bf16x8 b0 = *reinterpret_cast<const bf16x8*>(kr + off);
;     bf16x8 b1 = *reinterpret_cast<const bf16x8*>(kr + 32 * 128 + off);
;     p0 = __builtin_amdgcn_mfma_f32_32x32x16_bf16(b0, qr[d0], p0, 0, 0, 0);
;     p1 = __builtin_amdgcn_mfma_f32_32x32x16_bf16(b1, qr[d0], p1, 0, 0, 0); }
;   __builtin_amdgcn_s_setprio(0);
; }
	v_mfma_f32_32x32x16_bf16 v[16:31], v[40:43], v[132:135], v[16:31]
	v_bitop3_b32 v40, v207, v48, 4 bitop3:0x36
	v_lshlrev_b32_e32 v216, 4, v40
	v_mfma_f32_32x32x16_bf16 v[80:95], v[44:47], v[132:135], v[80:95]
	v_or_b32_e32 v44, v213, v216
	ds_read_b128 v[40:43], v44 offset:16384
	ds_read_b128 v[44:47], v44 offset:24576
	s_waitcnt lgkmcnt(0)
	v_mfma_f32_32x32x16_bf16 v[16:31], v[40:43], v[136:139], v[16:31]
	v_bitop3_b32 v40, v207, v48, 6 bitop3:0x36
	v_lshlrev_b32_e32 v217, 4, v40
	v_mfma_f32_32x32x16_bf16 v[80:95], v[44:47], v[136:139], v[80:95]
	v_or_b32_e32 v44, v213, v217
	ds_read_b128 v[40:43], v44 offset:16384
	ds_read_b128 v[44:47], v44 offset:24576
	s_waitcnt lgkmcnt(0)
	v_mfma_f32_32x32x16_bf16 v[16:31], v[40:43], v[140:143], v[16:31]
	v_bitop3_b32 v40, v207, v48, 8 bitop3:0x36
	v_lshlrev_b32_e32 v218, 4, v40
	v_mfma_f32_32x32x16_bf16 v[80:95], v[44:47], v[140:143], v[80:95]
	v_or_b32_e32 v44, v213, v218
	ds_read_b128 v[40:43], v44 offset:16384
	ds_read_b128 v[44:47], v44 offset:24576
	s_waitcnt lgkmcnt(0)
	v_mfma_f32_32x32x16_bf16 v[16:31], v[40:43], v[144:147], v[16:31]
	v_bitop3_b32 v40, v207, v48, 10 bitop3:0x36
	v_lshlrev_b32_e32 v219, 4, v40
	v_mfma_f32_32x32x16_bf16 v[80:95], v[44:47], v[144:147], v[80:95]
	v_or_b32_e32 v44, v213, v219
	ds_read_b128 v[40:43], v44 offset:16384
	ds_read_b128 v[44:47], v44 offset:24576
	s_waitcnt lgkmcnt(0)
	v_mfma_f32_32x32x16_bf16 v[16:31], v[40:43], v[148:151], v[16:31]
	v_bitop3_b32 v40, v207, v48, 12 bitop3:0x36
	v_lshlrev_b32_e32 v220, 4, v40
	v_mfma_f32_32x32x16_bf16 v[80:95], v[44:47], v[148:151], v[80:95]
	v_or_b32_e32 v44, v213, v220
	ds_read_b128 v[40:43], v44 offset:16384
	ds_read_b128 v[44:47], v44 offset:24576
	s_waitcnt lgkmcnt(0)
	v_mfma_f32_32x32x16_bf16 v[16:31], v[40:43], v[152:155], v[16:31]
	v_bitop3_b32 v40, v207, v48, 14 bitop3:0x36
	v_lshlrev_b32_e32 v221, 4, v40
	v_bfe_u32 v48, v96, 1, 3
	v_mfma_f32_32x32x16_bf16 v[80:95], v[44:47], v[152:155], v[80:95]
	v_or_b32_e32 v44, v213, v221
	ds_read_b128 v[40:43], v44 offset:16384
	ds_read_b128 v[44:47], v44 offset:24576
	s_waitcnt lgkmcnt(0)
	v_mfma_f32_32x32x16_bf16 v[16:31], v[40:43], v[156:159], v[16:31]
	v_lshrrev_b32_e32 v40, 1, v96
	v_bitop3_b32 v40, v207, v40, 7 bitop3:0x78
	v_lshlrev_b32_e32 v223, 4, v40
	v_mfma_f32_32x32x16_bf16 v[80:95], v[44:47], v[156:159], v[80:95]
	v_or_b32_e32 v44, v222, v223
	ds_read_b128 v[40:43], v44 offset:32768
	ds_read_b128 v[44:47], v44 offset:36864
	s_waitcnt lgkmcnt(0)
	v_mfma_f32_32x32x16_bf16 v[16:31], v[40:43], v[164:167], v[16:31]
	v_bitop3_b32 v40, v207, v48, 2 bitop3:0x36
	v_lshlrev_b32_e32 v224, 4, v40
	v_mfma_f32_32x32x16_bf16 v[80:95], v[44:47], v[164:167], v[80:95]
	v_or_b32_e32 v44, v222, v224
	ds_read_b128 v[40:43], v44 offset:32768
	ds_read_b128 v[44:47], v44 offset:36864
	s_waitcnt lgkmcnt(0)
	v_mfma_f32_32x32x16_bf16 v[16:31], v[40:43], v[172:175], v[16:31]
	v_bitop3_b32 v40, v207, v48, 4 bitop3:0x36
	v_lshlrev_b32_e32 v225, 4, v40
	v_mfma_f32_32x32x16_bf16 v[80:95], v[44:47], v[172:175], v[80:95]
	v_or_b32_e32 v44, v222, v225
	ds_read_b128 v[40:43], v44 offset:32768
	ds_read_b128 v[44:47], v44 offset:36864
	s_waitcnt lgkmcnt(0)
	v_mfma_f32_32x32x16_bf16 v[16:31], v[40:43], v[160:163], v[16:31]
	v_bitop3_b32 v40, v207, v48, 6 bitop3:0x36
	v_lshlrev_b32_e32 v226, 4, v40
	v_mfma_f32_32x32x16_bf16 v[80:95], v[44:47], v[160:163], v[80:95]
	v_or_b32_e32 v44, v222, v226
	ds_read_b128 v[40:43], v44 offset:32768
	ds_read_b128 v[44:47], v44 offset:36864
	s_waitcnt lgkmcnt(0)
	v_mfma_f32_32x32x16_bf16 v[16:31], v[40:43], v[168:171], v[16:31]
	v_mfma_f32_32x32x16_bf16 v[80:95], v[44:47], v[168:171], v[80:95]
	s_setprio 0
	s_nop 9
	v_exp_f32_e32 v240, v16
	v_exp_f32_e32 v242, v17
	v_exp_f32_e32 v238, v18
	v_exp_f32_e32 v241, v19
	v_exp_f32_e32 v236, v20
	v_exp_f32_e32 v239, v21
	v_exp_f32_e32 v235, v22
	v_exp_f32_e32 v237, v23
	v_exp_f32_e32 v232, v24
	v_exp_f32_e32 v234, v25
	v_exp_f32_e32 v230, v26
	v_exp_f32_e32 v233, v27
	v_exp_f32_e32 v228, v28
	v_exp_f32_e32 v231, v29
	v_exp_f32_e32 v227, v30
	v_exp_f32_e32 v229, v31
	s_or_b32 s48, s63, s80
	s_mov_b32 s49, s64
	v_lshl_add_u64 v[178:179], s[48:49], 0, v[34:35]
	s_or_b32 s48, s59, s79
	s_mov_b32 s49, s60
	v_lshl_add_u64 v[180:181], s[48:49], 0, v[38:39]
	v_lshl_add_u64 v[182:183], s[48:49], 0, v[36:37]
	v_lshl_add_u64 v[184:185], s[48:49], 0, v[176:177]
	v_lshl_add_u64 v[186:187], s[48:49], 0, v[32:33]
	s_mov_b32 s54, 0x14000
	s_mov_b32 s48, -1
	s_mov_b32 s49, 0xa000
	v_mov_b32_e32 v176, 0
	v_mov_b32_e32 v16, 0
	v_mov_b32_e32 v17, v177
	v_mov_b32_e32 v18, v177
	v_mov_b32_e32 v19, v177
	v_mov_b32_e32 v20, v177
	v_mov_b32_e32 v21, v177
	v_mov_b32_e32 v22, v177
	v_mov_b32_e32 v23, v177
	v_mov_b32_e32 v24, v177
	v_mov_b32_e32 v25, v177
	v_mov_b32_e32 v26, v177
	v_mov_b32_e32 v27, v177
	v_mov_b32_e32 v28, v177
	v_mov_b32_e32 v29, v177
	v_mov_b32_e32 v30, v177
	v_mov_b32_e32 v31, v177
	v_mov_b32_e32 v32, 0
	v_mov_b32_e32 v34, v177
	v_mov_b32_e32 v36, v177
	v_mov_b32_e32 v38, v177
	v_mov_b32_e32 v40, v177
	v_mov_b32_e32 v41, v177
	v_mov_b32_e32 v42, v177
	v_mov_b32_e32 v43, v177
	v_mov_b32_e32 v44, v177
	v_mov_b32_e32 v45, v177
	v_mov_b32_e32 v46, v177
	v_mov_b32_e32 v47, v177
	v_mov_b32_e32 v48, 0
	v_mov_b32_e32 v49, v177
	v_mov_b32_e32 v50, v177
	v_mov_b32_e32 v51, v177
	v_mov_b32_e32 v52, v177
	v_mov_b32_e32 v53, v177
	v_mov_b32_e32 v54, v177
	v_mov_b32_e32 v55, v177
	v_mov_b32_e32 v56, v177
	v_mov_b32_e32 v57, v177
	v_mov_b32_e32 v58, v177
	v_mov_b32_e32 v59, v177
	v_mov_b32_e32 v60, v177
	v_mov_b32_e32 v61, v177
	v_mov_b32_e32 v62, v177
	v_mov_b32_e32 v63, v177
	v_mov_b32_e32 v64, 0
	v_mov_b32_e32 v65, v177
	v_mov_b32_e32 v66, v177
	v_mov_b32_e32 v67, v177
	v_mov_b32_e32 v68, v177
	v_mov_b32_e32 v69, v177
	v_mov_b32_e32 v70, v177
	v_mov_b32_e32 v71, v177
	v_mov_b32_e32 v72, v177
	v_mov_b32_e32 v73, v177
	v_mov_b32_e32 v74, v177
	v_mov_b32_e32 v75, v177
	v_mov_b32_e32 v76, v177
	v_mov_b32_e32 v77, v177
	v_mov_b32_e32 v78, v177
	v_mov_b32_e32 v79, v177
	s_add_u32 s88, s26, 0x16a80000
	s_addc_u32 s89, s27, 0
	s_add_u32 s90, s26, 0x2aa20000
	s_addc_u32 s91, s27, 0
	s_add_u32 s92, s26, 0x16a80100
	s_addc_u32 s93, s27, 0
; __device__ __forceinline__ void finishSM(f32x16& p0, f32x16& p1, float& l_reg, bf16x8& pa0, bf16x8& pa1, bf16x8& pa2, bf16x8& pa3) {
; #pragma unroll
;   for (int r = 0; r < 16; ++r) p1[r] = __builtin_amdgcn_exp2f(p1[r]);
;   float ps = 0;
; #pragma unroll
;   for (int r = 0; r < 16; ++r) ps += p0[r];
; #pragma unroll
;   for (int r = 0; r < 16; ++r) ps += p1[r];
;   { auto rr = __builtin_amdgcn_permlane32_swap(__float_as_uint(ps), __float_as_uint(ps), false, false);
;     ps = __uint_as_float(rr[0]) + __uint_as_float(rr[1]); }
;   l_reg += ps;
;     ...
;   PK4(p0, 0, pa0); PK4(p0, 8, pa1); PK4(p1, 0, pa2); PK4(p1, 8, pa3);
;     ...
; }
; __device__ __forceinline__ void qkt(f32x16& p0, f32x16& p1, const char* Ks, const bf16x8* qr, int r32, int hi, float negM) {
; #pragma unroll
;   for (int r = 0; r < 16; ++r) { p0[r] = negM; p1[r] = negM; }
;   __builtin_amdgcn_s_setprio(1);
;   const char* kn = Ks + r32 * 256; const int xn = r32 & 15;
; #pragma unroll
;   for (int d0 = 0; d0 < 8; ++d0) { const int off = ((d0 * 2 + hi) ^ xn) << 4;
;     bf16x8 b0 = *reinterpret_cast<const bf16x8*>(kn + off);
;     bf16x8 b1 = *reinterpret_cast<const bf16x8*>(kn + 32 * 256 + off);
;     p0 = __builtin_amdgcn_mfma_f32_32x32x16_bf16(b0, qr[d0], p0, 0, 0, 0);
;     p1 = __builtin_amdgcn_mfma_f32_32x32x16_bf16(b1, qr[d0], p1, 0, 0, 0); }
;   const char* kr = Ks + KROPE_OFF + r32 * 128; const int xr = (r32 >> 1) & 7;
; #pragma unroll
;   for (int d0 = 8; d0 < 12; ++d0) { const int off = (((d0 - 8) * 2 + hi) ^ xr) << 4;
;     bf16x8 b0 = *reinterpret_cast<const bf16x8*>(kr + off);
;     bf16x8 b1 = *reinterpret_cast<const bf16x8*>(kr + 32 * 128 + off);
;     p0 = __builtin_amdgcn_mfma_f32_32x32x16_bf16(b0, qr[d0], p0, 0, 0, 0);
;     p1 = __builtin_amdgcn_mfma_f32_32x32x16_bf16(b1, qr[d0], p1, 0, 0, 0); }
;   __builtin_amdgcn_s_setprio(0);
; }
.LBB0_719:
	s_waitcnt vmcnt(0)
	s_waitcnt lgkmcnt(0)
	s_mov_b32 s51, s54
	s_barrier
	s_setprio 1
	v_add_u32_e32 v243, s49, v213
	v_add_u32_e32 v100, v243, v214
	ds_read_b128 v[96:99], v100 offset:16384
	ds_read_b128 v[244:247], v100 offset:24576
	v_add_u32_e32 v248, v243, v215
	s_add_u32 s54, s51, s87
	v_exp_f32_e32 v80, v80
	v_add_f32_e32 v252, 0, v240
	v_add_f32_e32 v252, v242, v252
	s_waitcnt lgkmcnt(0)
	v_mfma_f32_32x32x16_bf16 v[112:127], v[96:99], v[128:131], v[0:15]
	v_exp_f32_e32 v81, v81
	v_add_f32_e32 v252, v238, v252
	v_add_f32_e32 v252, v241, v252
	v_mfma_f32_32x32x16_bf16 v[96:111], v[244:247], v[128:131], v[0:15]
	ds_read_b128 v[244:247], v248 offset:16384
	ds_read_b128 v[248:251], v248 offset:24576
	s_add_u32 m0, s54, 0x4000
	s_nop 0
	global_load_lds_dwordx4 v184, s[88:89]
	v_exp_f32_e32 v82, v82
	v_add_f32_e32 v252, v236, v252
	v_add_f32_e32 v252, v239, v252
	s_waitcnt lgkmcnt(0)
	v_mfma_f32_32x32x16_bf16 v[112:127], v[244:247], v[132:135], v[112:127]
	v_exp_f32_e32 v83, v83
	v_add_f32_e32 v252, v235, v252
	v_add_f32_e32 v252, v237, v252
	v_mfma_f32_32x32x16_bf16 v[96:111], v[248:251], v[132:135], v[96:111]
	v_add_u32_e32 v248, v243, v216
	ds_read_b128 v[244:247], v248 offset:16384
	ds_read_b128 v[248:251], v248 offset:24576
	s_add_u32 m0, s54, 0x6000
	s_nop 0
	global_load_lds_dwordx4 v186, s[88:89]
	v_exp_f32_e32 v84, v84
	v_add_f32_e32 v252, v232, v252
	v_add_f32_e32 v252, v234, v252
	s_waitcnt lgkmcnt(0)
	v_mfma_f32_32x32x16_bf16 v[112:127], v[244:247], v[136:139], v[112:127]
	v_exp_f32_e32 v85, v85
	v_add_f32_e32 v252, v230, v252
	v_add_f32_e32 v252, v233, v252
	v_mfma_f32_32x32x16_bf16 v[96:111], v[248:251], v[136:139], v[96:111]
	v_add_u32_e32 v248, v243, v217
	ds_read_b128 v[244:247], v248 offset:16384
	ds_read_b128 v[248:251], v248 offset:24576
	s_add_u32 m0, s54, 0x8000
	s_nop 0
	global_load_lds_dwordx4 v178, s[90:91]
	v_exp_f32_e32 v86, v86
	v_add_f32_e32 v252, v228, v252
	v_add_f32_e32 v252, v231, v252
	s_waitcnt lgkmcnt(0)
	v_mfma_f32_32x32x16_bf16 v[112:127], v[244:247], v[140:143], v[112:127]
	v_exp_f32_e32 v87, v87
	v_add_f32_e32 v252, v227, v252
	v_add_f32_e32 v252, v229, v252
	v_mfma_f32_32x32x16_bf16 v[96:111], v[248:251], v[140:143], v[96:111]
	v_add_u32_e32 v248, v243, v218
	ds_read_b128 v[244:247], v248 offset:16384
	ds_read_b128 v[248:251], v248 offset:24576
	s_mov_b32 m0, s54
	s_nop 0
	global_load_lds_dwordx4 v182, s[92:93]
	v_exp_f32_e32 v88, v88
	v_add_f32_e32 v252, v80, v252
	v_exp_f32_e32 v89, v89
	s_waitcnt lgkmcnt(0)
	v_mfma_f32_32x32x16_bf16 v[112:127], v[244:247], v[144:147], v[112:127]
	v_add_f32_e32 v252, v81, v252
	v_exp_f32_e32 v90, v90
	v_add_f32_e32 v252, v82, v252
	v_mfma_f32_32x32x16_bf16 v[96:111], v[248:251], v[144:147], v[96:111]
	v_add_u32_e32 v248, v243, v219
	ds_read_b128 v[244:247], v248 offset:16384
	ds_read_b128 v[248:251], v248 offset:24576
	s_add_u32 m0, s54, 0x2000
	s_nop 0
	global_load_lds_dwordx4 v180, s[92:93]
	s_add_u32 s88, s88, 0x40000
	s_addc_u32 s89, s89, 0
	s_add_u32 s90, s90, 0x10000
	s_addc_u32 s91, s91, 0
	s_add_u32 s92, s92, 0x40000
	s_addc_u32 s93, s93, 0
	v_exp_f32_e32 v91, v91
	v_add_f32_e32 v252, v83, v252
	v_exp_f32_e32 v92, v92
	s_waitcnt lgkmcnt(0)
	v_mfma_f32_32x32x16_bf16 v[112:127], v[244:247], v[148:151], v[112:127]
	v_add_f32_e32 v252, v84, v252
	v_exp_f32_e32 v93, v93
	v_add_f32_e32 v252, v85, v252
	v_mfma_f32_32x32x16_bf16 v[96:111], v[248:251], v[148:151], v[96:111]
	v_add_u32_e32 v248, v243, v220
	ds_read_b128 v[244:247], v248 offset:16384
	ds_read_b128 v[248:251], v248 offset:24576
	v_add_u32_e32 v243, v243, v221
	v_exp_f32_e32 v94, v94
	v_add_f32_e32 v252, v86, v252
	v_exp_f32_e32 v95, v95
	s_waitcnt lgkmcnt(0)
	v_mfma_f32_32x32x16_bf16 v[112:127], v[244:247], v[152:155], v[112:127]
	v_add_f32_e32 v252, v87, v252
	v_add_f32_e32 v252, v88, v252
	v_add_f32_e32 v252, v89, v252
	v_mfma_f32_32x32x16_bf16 v[96:111], v[248:251], v[152:155], v[96:111]
	ds_read_b128 v[244:247], v243 offset:16384
	ds_read_b128 v[248:251], v243 offset:24576
	v_add_u32_e32 v243, s49, v222
	v_add_f32_e32 v252, v90, v252
	v_add_f32_e32 v252, v91, v252
	v_add_f32_e32 v252, v92, v252
	s_waitcnt lgkmcnt(0)
	v_mfma_f32_32x32x16_bf16 v[112:127], v[244:247], v[156:159], v[112:127]
	v_add_f32_e32 v252, v93, v252
	v_add_f32_e32 v252, v94, v252
	v_add_f32_e32 v252, v95, v252
	v_mfma_f32_32x32x16_bf16 v[96:111], v[248:251], v[156:159], v[96:111]
	v_add_u32_e32 v248, v243, v223
	ds_read_b128 v[244:247], v248 offset:32768
	ds_read_b128 v[248:251], v248 offset:36864
	v_mov_b32_e32 v253, v252
	v_cvt_pk_bf16_f32 v95, v94, v95
	v_cvt_pk_bf16_f32 v94, v92, v93
	s_waitcnt lgkmcnt(0)
	v_mfma_f32_32x32x16_bf16 v[112:127], v[244:247], v[164:167], v[112:127]
	v_permlane32_swap_b32_e32 v252, v253
	v_cvt_pk_bf16_f32 v93, v90, v91
	v_cvt_pk_bf16_f32 v92, v88, v89
	v_mfma_f32_32x32x16_bf16 v[96:111], v[248:251], v[164:167], v[96:111]
	v_add_u32_e32 v248, v243, v224
	ds_read_b128 v[244:247], v248 offset:32768
	ds_read_b128 v[248:251], v248 offset:36864
	v_add_f32_e32 v252, v252, v253
	v_cvt_pk_bf16_f32 v91, v86, v87
	v_add_f32_e32 v176, v176, v252
	s_waitcnt lgkmcnt(0)
	v_mfma_f32_32x32x16_bf16 v[112:127], v[244:247], v[172:175], v[112:127]
	v_cvt_pk_bf16_f32 v90, v84, v85
	v_cvt_pk_bf16_f32 v89, v82, v83
	v_cvt_pk_bf16_f32 v88, v80, v81
	v_mfma_f32_32x32x16_bf16 v[96:111], v[248:251], v[172:175], v[96:111]
	v_add_u32_e32 v248, v243, v225
	ds_read_b128 v[244:247], v248 offset:32768
	ds_read_b128 v[248:251], v248 offset:36864
	v_add_u32_e32 v243, v243, v226
	v_cvt_pk_bf16_f32 v80, v240, v242
	v_cvt_pk_bf16_f32 v81, v238, v241
	v_cvt_pk_bf16_f32 v82, v236, v239
	s_waitcnt lgkmcnt(0)
; #define SBAR() __builtin_amdgcn_sched_barrier(0)
; template <int OFF> __device__ __forceinline__ s16x4 tr_read(int vb) {
;   s16x4 r; asm volatile("ds_read_b64_tr_b16 %0, %1 offset:%2" : "=&v"(r) : "v"(vb), "i"(OFF) : "memory"); return r;
; }
; template <int D0> __device__ __forceinline__ void pv_one(f32x16& od, int vb, bf16x8 pa0, bf16x8 pa1, bf16x8 pa2, bf16x8 pa3) {
;   const s16x4 l0 = tr_read<v_rd_off(D0, 0, 0)>(vb), h0 = tr_read<v_rd_off(D0, 0, 1)>(vb), l1 = tr_read<v_rd_off(D0, 1, 0)>(vb), h1 = tr_read<v_rd_off(D0, 1, 1)>(vb);
;   const s16x4 l2 = tr_read<v_rd_off(D0, 2, 0)>(vb), h2 = tr_read<v_rd_off(D0, 2, 1)>(vb), l3 = tr_read<v_rd_off(D0, 3, 0)>(vb), h3 = tr_read<v_rd_off(D0, 3, 1)>(vb);
;   asm volatile("s_waitcnt lgkmcnt(0)" ::: "memory"); SBAR();
;     ...
;   od = __builtin_amdgcn_mfma_f32_32x32x16_bf16(pa0, PK(l0, h0), od, 0, 0, 0);
;   od = __builtin_amdgcn_mfma_f32_32x32x16_bf16(pa1, PK(l1, h1), od, 0, 0, 0);
;   od = __builtin_amdgcn_mfma_f32_32x32x16_bf16(pa2, PK(l2, h2), od, 0, 0, 0);
;   od = __builtin_amdgcn_mfma_f32_32x32x16_bf16(pa3, PK(l3, h3), od, 0, 0, 0);
;     ...
; }
; __device__ __forceinline__ void pv_d0(f32x16* o, int vb, bf16x8 pa0, bf16x8 pa1, bf16x8 pa2, bf16x8 pa3) {
;   pv_one<0>(o[0], vb, pa0, pa1, pa2, pa3); pv_one<1>(o[1], vb, pa0, pa1, pa2, pa3); pv_one<2>(o[2], vb, pa0, pa1, pa2, pa3); pv_one<3>(o[3], vb, pa0, pa1, pa2, pa3);
; }
; __device__ __forceinline__ void attn_body(const u16* __restrict__ Qb, const u16* __restrict__ Kn, const u16* __restrict__ Kr,
;                                           u16* __restrict__ Ob, char* lds, int tid, const float* __restrict__ gq_, const float* __restrict__ tab_, int qpos0, float negM) {
;     ...
;   for (int j = 1; j + 1 < NT; j += 2) {
;     WAITV(0); asm volatile("s_waitcnt lgkmcnt(0)" ::: "memory"); TBAR();
;     AISSUE((j + 1) * KVBLK, nxt);
;     qkt(pB0, pB1, lds + cur + KOFF, qr, r32, hi, negM);
;     finishSM(pA0, pA1, l_reg, pa0, pa1, pa2, pa3); SBAR();
;     pv_d0(o, vrb + prv, pa0, pa1, pa2, pa3); partialSM(pB0);
;     { const int t_ = prv; prv = cur; cur = nxt; nxt = t_; }
;     WAITV(0); asm volatile("s_waitcnt lgkmcnt(0)" ::: "memory"); TBAR();
;     if (j + 2 < NT) AISSUE((j + 2) * KVBLK, nxt);
;     qkt(pA0, pA1, lds + cur + KOFF, qr, r32, hi, negM);
;     finishSM(pB0, pB1, l_reg, pa0, pa1, pa2, pa3); SBAR();
;     pv_d0(o, vrb + prv, pa0, pa1, pa2, pa3); partialSM(pA0);
	v_mfma_f32_32x32x16_bf16 v[112:127], v[244:247], v[160:163], v[112:127]
	v_cvt_pk_bf16_f32 v83, v235, v237
	v_cvt_pk_bf16_f32 v84, v232, v234
	v_cvt_pk_bf16_f32 v85, v230, v233
	v_mfma_f32_32x32x16_bf16 v[96:111], v[248:251], v[160:163], v[96:111]
	ds_read_b128 v[244:247], v243 offset:32768
	ds_read_b128 v[248:251], v243 offset:36864
	v_cvt_pk_bf16_f32 v86, v228, v231
	v_cvt_pk_bf16_f32 v87, v227, v229
	v_permlane32_swap_b32_e32 v88, v90
	s_waitcnt lgkmcnt(0)
	v_add_u32_e32 v198, s50, v212
	ds_read_b64_tr_b16 v[228:229], v198 offset:0
	ds_read_b64_tr_b16 v[230:231], v198 offset:0x800
	ds_read_b64_tr_b16 v[232:233], v198 offset:0x1000
	ds_read_b64_tr_b16 v[234:235], v198 offset:0x1800
	ds_read_b64_tr_b16 v[236:237], v198 offset:0x2000
	ds_read_b64_tr_b16 v[238:239], v198 offset:0x2800
	ds_read_b64_tr_b16 v[240:241], v198 offset:0x3000
	ds_read_b64_tr_b16 v[242:243], v198 offset:0x3800
	v_mfma_f32_32x32x16_bf16 v[112:127], v[244:247], v[168:171], v[112:127]
	v_permlane32_swap_b32_e32 v89, v91
	v_permlane32_swap_b32_e32 v92, v94
	v_permlane32_swap_b32_e32 v93, v95
	v_mfma_f32_32x32x16_bf16 v[96:111], v[248:251], v[168:171], v[96:111]
	s_setprio 0
	v_permlane32_swap_b32_e32 v80, v82
	v_permlane32_swap_b32_e32 v81, v83
	v_permlane32_swap_b32_e32 v84, v86
	v_permlane32_swap_b32_e32 v85, v87
	s_waitcnt lgkmcnt(0)
	s_nop 0
	v_mfma_f32_32x32x16_bf16 v[64:79], v[80:83], v[228:231], v[64:79]
	ds_read_b64_tr_b16 v[228:229], v198 offset:0x200
	ds_read_b64_tr_b16 v[230:231], v198 offset:0xa00
	v_mfma_f32_32x32x16_bf16 v[64:79], v[84:87], v[232:235], v[64:79]
	ds_read_b64_tr_b16 v[232:233], v198 offset:0x1200
	ds_read_b64_tr_b16 v[234:235], v198 offset:0x1a00
	v_mfma_f32_32x32x16_bf16 v[64:79], v[88:91], v[236:239], v[64:79]
	ds_read_b64_tr_b16 v[236:237], v198 offset:0x2200
	ds_read_b64_tr_b16 v[238:239], v198 offset:0x2a00
	ds_read_b64_tr_b16 v[244:245], v198 offset:0x3200
	ds_read_b64_tr_b16 v[246:247], v198 offset:0x3a00
	s_waitcnt lgkmcnt(0)
	v_mfma_f32_32x32x16_bf16 v[64:79], v[92:95], v[240:243], v[64:79]
	v_mfma_f32_32x32x16_bf16 v[48:63], v[80:83], v[228:231], v[48:63]
	ds_read_b64_tr_b16 v[228:229], v198 offset:0x400
	ds_read_b64_tr_b16 v[230:231], v198 offset:0xc00
	v_mfma_f32_32x32x16_bf16 v[48:63], v[84:87], v[232:235], v[48:63]
	ds_read_b64_tr_b16 v[232:233], v198 offset:0x1400
	ds_read_b64_tr_b16 v[234:235], v198 offset:0x1c00
	v_mfma_f32_32x32x16_bf16 v[48:63], v[88:91], v[236:239], v[48:63]
	ds_read_b64_tr_b16 v[236:237], v198 offset:0x2400
	ds_read_b64_tr_b16 v[238:239], v198 offset:0x2c00
	ds_read_b64_tr_b16 v[240:241], v198 offset:0x3400
	ds_read_b64_tr_b16 v[242:243], v198 offset:0x3c00
	s_waitcnt lgkmcnt(0)
	v_mfma_f32_32x32x16_bf16 v[48:63], v[92:95], v[244:247], v[48:63]
	v_mfma_f32_32x32x16_bf16 v[32:47], v[80:83], v[228:231], v[32:47]
	ds_read_b64_tr_b16 v[228:229], v198 offset:0x600
	ds_read_b64_tr_b16 v[230:231], v198 offset:0xe00
	v_mfma_f32_32x32x16_bf16 v[32:47], v[84:87], v[232:235], v[32:47]
	ds_read_b64_tr_b16 v[232:233], v198 offset:0x1600
	ds_read_b64_tr_b16 v[234:235], v198 offset:0x1e00
	v_mfma_f32_32x32x16_bf16 v[32:47], v[88:91], v[236:239], v[32:47]
	ds_read_b64_tr_b16 v[236:237], v198 offset:0x2600
	ds_read_b64_tr_b16 v[238:239], v198 offset:0x2e00
	ds_read_b64_tr_b16 v[244:245], v198 offset:0x3600
	ds_read_b64_tr_b16 v[246:247], v198 offset:0x3e00
	s_waitcnt lgkmcnt(0)
	v_mfma_f32_32x32x16_bf16 v[32:47], v[92:95], v[240:243], v[32:47]
	v_mfma_f32_32x32x16_bf16 v[16:31], v[80:83], v[228:231], v[16:31]
	v_exp_f32_e32 v227, v114
	v_exp_f32_e32 v228, v115
	v_exp_f32_e32 v229, v116
	v_exp_f32_e32 v230, v117
	v_exp_f32_e32 v231, v118
	v_exp_f32_e32 v240, v127
	s_waitcnt vmcnt(0)
	v_mfma_f32_32x32x16_bf16 v[16:31], v[84:87], v[232:235], v[16:31]
	v_exp_f32_e32 v232, v119
	v_exp_f32_e32 v233, v120
	v_exp_f32_e32 v234, v121
	v_exp_f32_e32 v235, v122
	s_waitcnt lgkmcnt(0)
	v_exp_f32_e32 v198, v112
	v_exp_f32_e32 v199, v113
	v_mfma_f32_32x32x16_bf16 v[16:31], v[88:91], v[236:239], v[16:31]
	v_exp_f32_e32 v236, v123
	v_exp_f32_e32 v237, v124
	v_exp_f32_e32 v238, v125
	v_exp_f32_e32 v239, v126
	s_barrier
	v_mfma_f32_32x32x16_bf16 v[16:31], v[92:95], v[244:247], v[16:31]
	s_setprio 1
	v_add_u32_e32 v243, s51, v213
	v_add_u32_e32 v84, v243, v214
	ds_read_b128 v[80:83], v84 offset:16384
	ds_read_b128 v[244:247], v84 offset:24576
	v_add_u32_e32 v248, v243, v215
	s_add_u32 s54, s50, s87
	v_exp_f32_e32 v96, v96
	v_add_f32_e32 v252, 0, v198
	v_add_f32_e32 v252, v199, v252
	s_waitcnt lgkmcnt(0)
	v_mfma_f32_32x32x16_bf16 v[112:127], v[80:83], v[128:131], v[0:15]
	v_exp_f32_e32 v97, v97
	v_add_f32_e32 v252, v227, v252
	v_add_f32_e32 v252, v228, v252
	v_mfma_f32_32x32x16_bf16 v[80:95], v[244:247], v[128:131], v[0:15]
	ds_read_b128 v[244:247], v248 offset:16384
	ds_read_b128 v[248:251], v248 offset:24576
	s_add_u32 m0, s54, 0x4000
	s_nop 0
	global_load_lds_dwordx4 v184, s[88:89]
	v_exp_f32_e32 v98, v98
	v_add_f32_e32 v252, v229, v252
	v_add_f32_e32 v252, v230, v252
	s_waitcnt lgkmcnt(0)
	v_mfma_f32_32x32x16_bf16 v[80:95], v[248:251], v[132:135], v[80:95]
	v_exp_f32_e32 v99, v99
	v_add_f32_e32 v252, v231, v252
	v_add_f32_e32 v252, v232, v252
	v_add_u32_e32 v248, v243, v216
	v_mfma_f32_32x32x16_bf16 v[112:127], v[244:247], v[132:135], v[112:127]
	ds_read_b128 v[244:247], v248 offset:16384
	ds_read_b128 v[248:251], v248 offset:24576
	s_add_u32 m0, s54, 0x6000
	s_nop 0
	global_load_lds_dwordx4 v186, s[88:89]
	v_exp_f32_e32 v100, v100
	v_add_f32_e32 v252, v233, v252
	v_add_f32_e32 v252, v234, v252
	s_waitcnt lgkmcnt(0)
; __device__ __forceinline__ void finishSM(f32x16& p0, f32x16& p1, float& l_reg, bf16x8& pa0, bf16x8& pa1, bf16x8& pa2, bf16x8& pa3) {
; #pragma unroll
;   for (int r = 0; r < 16; ++r) p1[r] = __builtin_amdgcn_exp2f(p1[r]);
;   float ps = 0;
; #pragma unroll
;   for (int r = 0; r < 16; ++r) ps += p0[r];
; #pragma unroll
;   for (int r = 0; r < 16; ++r) ps += p1[r];
;   { auto rr = __builtin_amdgcn_permlane32_swap(__float_as_uint(ps), __float_as_uint(ps), false, false);
;     ps = __uint_as_float(rr[0]) + __uint_as_float(rr[1]); }
;   l_reg += ps;
;     ...
;   PK4(p0, 0, pa0); PK4(p0, 8, pa1); PK4(p1, 0, pa2); PK4(p1, 8, pa3);
;     ...
; }
; __device__ __forceinline__ void qkt(f32x16& p0, f32x16& p1, const char* Ks, const bf16x8* qr, int r32, int hi, float negM) {
; #pragma unroll
;   for (int r = 0; r < 16; ++r) { p0[r] = negM; p1[r] = negM; }
;   __builtin_amdgcn_s_setprio(1);
;   const char* kn = Ks + r32 * 256; const int xn = r32 & 15;
; #pragma unroll
;   for (int d0 = 0; d0 < 8; ++d0) { const int off = ((d0 * 2 + hi) ^ xn) << 4;
;     bf16x8 b0 = *reinterpret_cast<const bf16x8*>(kn + off);
;     bf16x8 b1 = *reinterpret_cast<const bf16x8*>(kn + 32 * 256 + off);
;     p0 = __builtin_amdgcn_mfma_f32_32x32x16_bf16(b0, qr[d0], p0, 0, 0, 0);
;     p1 = __builtin_amdgcn_mfma_f32_32x32x16_bf16(b1, qr[d0], p1, 0, 0, 0); }
;   const char* kr = Ks + KROPE_OFF + r32 * 128; const int xr = (r32 >> 1) & 7;
; #pragma unroll
;   for (int d0 = 8; d0 < 12; ++d0) { const int off = (((d0 - 8) * 2 + hi) ^ xr) << 4;
;     bf16x8 b0 = *reinterpret_cast<const bf16x8*>(kr + off);
;     bf16x8 b1 = *reinterpret_cast<const bf16x8*>(kr + 32 * 128 + off);
;     p0 = __builtin_amdgcn_mfma_f32_32x32x16_bf16(b0, qr[d0], p0, 0, 0, 0);
;     p1 = __builtin_amdgcn_mfma_f32_32x32x16_bf16(b1, qr[d0], p1, 0, 0, 0); }
;   __builtin_amdgcn_s_setprio(0);
; }
	v_mfma_f32_32x32x16_bf16 v[80:95], v[248:251], v[136:139], v[80:95]
	v_exp_f32_e32 v101, v101
	v_add_f32_e32 v252, v235, v252
	v_add_f32_e32 v252, v236, v252
	v_add_u32_e32 v248, v243, v217
	v_mfma_f32_32x32x16_bf16 v[112:127], v[244:247], v[136:139], v[112:127]
	ds_read_b128 v[244:247], v248 offset:16384
	ds_read_b128 v[248:251], v248 offset:24576
	s_add_u32 m0, s54, 0x8000
	s_nop 0
	global_load_lds_dwordx4 v178, s[90:91]
	v_exp_f32_e32 v102, v102
	v_add_f32_e32 v252, v237, v252
	v_add_f32_e32 v252, v238, v252
	s_waitcnt lgkmcnt(0)
	v_mfma_f32_32x32x16_bf16 v[80:95], v[248:251], v[140:143], v[80:95]
	v_exp_f32_e32 v103, v103
	v_add_f32_e32 v252, v239, v252
	v_add_f32_e32 v252, v240, v252
	v_add_u32_e32 v248, v243, v218
	v_mfma_f32_32x32x16_bf16 v[112:127], v[244:247], v[140:143], v[112:127]
	ds_read_b128 v[244:247], v248 offset:16384
	ds_read_b128 v[248:251], v248 offset:24576
	s_mov_b32 m0, s54
	s_nop 0
	global_load_lds_dwordx4 v182, s[92:93]
	v_exp_f32_e32 v104, v104
	v_add_f32_e32 v252, v96, v252
	v_exp_f32_e32 v105, v105
	s_waitcnt lgkmcnt(0)
	v_mfma_f32_32x32x16_bf16 v[80:95], v[248:251], v[144:147], v[80:95]
	v_add_f32_e32 v252, v97, v252
	v_exp_f32_e32 v106, v106
	v_add_f32_e32 v252, v98, v252
	v_add_u32_e32 v248, v243, v219
	v_mfma_f32_32x32x16_bf16 v[112:127], v[244:247], v[144:147], v[112:127]
	ds_read_b128 v[244:247], v248 offset:16384
	ds_read_b128 v[248:251], v248 offset:24576
	s_add_u32 m0, s54, 0x2000
	s_nop 0
	global_load_lds_dwordx4 v180, s[92:93]
	s_add_u32 s88, s88, 0x40000
	s_addc_u32 s89, s89, 0
	s_add_u32 s90, s90, 0x10000
	s_addc_u32 s91, s91, 0
	s_add_u32 s92, s92, 0x40000
	s_addc_u32 s93, s93, 0
	v_exp_f32_e32 v107, v107
	v_add_f32_e32 v252, v99, v252
	v_exp_f32_e32 v108, v108
	s_waitcnt lgkmcnt(0)
	v_mfma_f32_32x32x16_bf16 v[80:95], v[248:251], v[148:151], v[80:95]
	v_add_f32_e32 v252, v100, v252
	v_exp_f32_e32 v109, v109
	v_add_f32_e32 v252, v101, v252
	v_add_u32_e32 v248, v243, v220
	v_mfma_f32_32x32x16_bf16 v[112:127], v[244:247], v[148:151], v[112:127]
	ds_read_b128 v[244:247], v248 offset:16384
	ds_read_b128 v[248:251], v248 offset:24576
	v_exp_f32_e32 v110, v110
	v_add_f32_e32 v252, v102, v252
	v_exp_f32_e32 v111, v111
	s_waitcnt lgkmcnt(0)
	v_mfma_f32_32x32x16_bf16 v[80:95], v[248:251], v[152:155], v[80:95]
	v_add_f32_e32 v252, v103, v252
	v_add_f32_e32 v252, v104, v252
	v_add_f32_e32 v252, v105, v252
	v_add_u32_e32 v248, v243, v221
	v_add_u32_e32 v243, s51, v222
	v_mfma_f32_32x32x16_bf16 v[112:127], v[244:247], v[152:155], v[112:127]
	ds_read_b128 v[244:247], v248 offset:16384
	ds_read_b128 v[248:251], v248 offset:24576
	v_add_f32_e32 v252, v106, v252
	v_add_f32_e32 v252, v107, v252
	v_add_f32_e32 v252, v108, v252
	s_waitcnt lgkmcnt(0)
	v_mfma_f32_32x32x16_bf16 v[80:95], v[248:251], v[156:159], v[80:95]
	v_add_f32_e32 v252, v109, v252
	v_add_f32_e32 v252, v110, v252
	v_add_f32_e32 v252, v111, v252
	v_add_u32_e32 v248, v243, v223
	v_mfma_f32_32x32x16_bf16 v[112:127], v[244:247], v[156:159], v[112:127]
	ds_read_b128 v[244:247], v248 offset:32768
	ds_read_b128 v[248:251], v248 offset:36864
	v_mov_b32_e32 v253, v252
	v_cvt_pk_bf16_f32 v111, v110, v111
	v_cvt_pk_bf16_f32 v110, v108, v109
	s_waitcnt lgkmcnt(0)
	v_mfma_f32_32x32x16_bf16 v[80:95], v[248:251], v[164:167], v[80:95]
	v_permlane32_swap_b32_e32 v252, v253
	v_cvt_pk_bf16_f32 v109, v106, v107
	v_cvt_pk_bf16_f32 v108, v104, v105
	v_add_u32_e32 v248, v243, v224
	v_mfma_f32_32x32x16_bf16 v[112:127], v[244:247], v[164:167], v[112:127]
	ds_read_b128 v[244:247], v248 offset:32768
	ds_read_b128 v[248:251], v248 offset:36864
	v_add_f32_e32 v252, v252, v253
	v_cvt_pk_bf16_f32 v107, v102, v103
	v_add_f32_e32 v176, v176, v252
	s_waitcnt lgkmcnt(0)
	v_mfma_f32_32x32x16_bf16 v[80:95], v[248:251], v[172:175], v[80:95]
	v_cvt_pk_bf16_f32 v106, v100, v101
	v_cvt_pk_bf16_f32 v105, v98, v99
	v_cvt_pk_bf16_f32 v104, v96, v97
	v_add_u32_e32 v248, v243, v225
	v_mfma_f32_32x32x16_bf16 v[112:127], v[244:247], v[172:175], v[112:127]
	ds_read_b128 v[244:247], v248 offset:32768
	ds_read_b128 v[248:251], v248 offset:36864
	v_cvt_pk_bf16_f32 v96, v198, v199
	v_cvt_pk_bf16_f32 v97, v227, v228
	v_cvt_pk_bf16_f32 v98, v229, v230
	s_waitcnt lgkmcnt(0)
	v_mfma_f32_32x32x16_bf16 v[80:95], v[248:251], v[160:163], v[80:95]
	v_cvt_pk_bf16_f32 v99, v231, v232
	v_cvt_pk_bf16_f32 v100, v233, v234
	v_cvt_pk_bf16_f32 v101, v235, v236
	v_add_u32_e32 v248, v243, v226
	v_mfma_f32_32x32x16_bf16 v[112:127], v[244:247], v[160:163], v[112:127]
	ds_read_b128 v[244:247], v248 offset:32768
	ds_read_b128 v[248:251], v248 offset:36864
	v_cvt_pk_bf16_f32 v102, v237, v238
	v_cvt_pk_bf16_f32 v103, v239, v240
	v_permlane32_swap_b32_e32 v104, v106
	s_waitcnt lgkmcnt(0)
	v_add_u32_e32 v196, s49, v212
	ds_read_b64_tr_b16 v[188:189], v196 offset:0
	ds_read_b64_tr_b16 v[190:191], v196 offset:0x800
	ds_read_b64_tr_b16 v[192:193], v196 offset:0x1000
	ds_read_b64_tr_b16 v[194:195], v196 offset:0x1800
	ds_read_b64_tr_b16 v[228:229], v196 offset:0x2000
	ds_read_b64_tr_b16 v[230:231], v196 offset:0x2800
	ds_read_b64_tr_b16 v[232:233], v196 offset:0x3000
	ds_read_b64_tr_b16 v[234:235], v196 offset:0x3800
	v_mfma_f32_32x32x16_bf16 v[80:95], v[248:251], v[168:171], v[80:95]
	v_permlane32_swap_b32_e32 v105, v107
	v_permlane32_swap_b32_e32 v108, v110
	v_permlane32_swap_b32_e32 v109, v111
	v_mfma_f32_32x32x16_bf16 v[112:127], v[244:247], v[168:171], v[112:127]
	s_setprio 0
	v_permlane32_swap_b32_e32 v96, v98
	v_permlane32_swap_b32_e32 v97, v99
	v_permlane32_swap_b32_e32 v100, v102
	v_permlane32_swap_b32_e32 v101, v103
	s_waitcnt lgkmcnt(0)
; #define SBAR() __builtin_amdgcn_sched_barrier(0)
; #define WAITV(n) asm volatile("s_waitcnt vmcnt(" #n ")" ::: "memory")
; #define TBAR() do { __builtin_amdgcn_s_barrier(); SBAR(); } while (0)
; template <int OFF> __device__ __forceinline__ s16x4 tr_read(int vb) {
;   s16x4 r; asm volatile("ds_read_b64_tr_b16 %0, %1 offset:%2" : "=&v"(r) : "v"(vb), "i"(OFF) : "memory"); return r;
; }
; template <int D0> __device__ __forceinline__ void pv_one(f32x16& od, int vb, bf16x8 pa0, bf16x8 pa1, bf16x8 pa2, bf16x8 pa3) {
;   const s16x4 l0 = tr_read<v_rd_off(D0, 0, 0)>(vb), h0 = tr_read<v_rd_off(D0, 0, 1)>(vb), l1 = tr_read<v_rd_off(D0, 1, 0)>(vb), h1 = tr_read<v_rd_off(D0, 1, 1)>(vb);
;   const s16x4 l2 = tr_read<v_rd_off(D0, 2, 0)>(vb), h2 = tr_read<v_rd_off(D0, 2, 1)>(vb), l3 = tr_read<v_rd_off(D0, 3, 0)>(vb), h3 = tr_read<v_rd_off(D0, 3, 1)>(vb);
;   asm volatile("s_waitcnt lgkmcnt(0)" ::: "memory"); SBAR();
;     ...
;   od = __builtin_amdgcn_mfma_f32_32x32x16_bf16(pa0, PK(l0, h0), od, 0, 0, 0);
;   od = __builtin_amdgcn_mfma_f32_32x32x16_bf16(pa1, PK(l1, h1), od, 0, 0, 0);
;   od = __builtin_amdgcn_mfma_f32_32x32x16_bf16(pa2, PK(l2, h2), od, 0, 0, 0);
;   od = __builtin_amdgcn_mfma_f32_32x32x16_bf16(pa3, PK(l3, h3), od, 0, 0, 0);
;     ...
; }
; __device__ __forceinline__ void pv_d0(f32x16* o, int vb, bf16x8 pa0, bf16x8 pa1, bf16x8 pa2, bf16x8 pa3) {
;   pv_one<0>(o[0], vb, pa0, pa1, pa2, pa3); pv_one<1>(o[1], vb, pa0, pa1, pa2, pa3); pv_one<2>(o[2], vb, pa0, pa1, pa2, pa3); pv_one<3>(o[3], vb, pa0, pa1, pa2, pa3);
; }
; __device__ __forceinline__ void attn_body(const u16* __restrict__ Qb, const u16* __restrict__ Kn, const u16* __restrict__ Kr,
;                                           u16* __restrict__ Ob, char* lds, int tid, const float* __restrict__ gq_, const float* __restrict__ tab_, int qpos0, float negM) {
;     ...
;     WAITV(0); asm volatile("s_waitcnt lgkmcnt(0)" ::: "memory"); TBAR();
;     if (j + 2 < NT) AISSUE((j + 2) * KVBLK, nxt);
;     qkt(pA0, pA1, lds + cur + KOFF, qr, r32, hi, negM);
;     finishSM(pB0, pB1, l_reg, pa0, pa1, pa2, pa3); SBAR();
;     pv_d0(o, vrb + prv, pa0, pa1, pa2, pa3); partialSM(pA0);
;     { const int t_ = prv; prv = cur; cur = nxt; nxt = t_; }
;   }
;   WAITV(0); asm volatile("s_waitcnt lgkmcnt(0)" ::: "memory"); TBAR();
;   qkt(pB0, pB1, lds + cur + KOFF, qr, r32, hi, negM);
	s_nop 0
	v_mfma_f32_32x32x16_bf16 v[64:79], v[96:99], v[188:191], v[64:79]
	ds_read_b64_tr_b16 v[188:189], v196 offset:0x200
	ds_read_b64_tr_b16 v[190:191], v196 offset:0xa00
	v_mfma_f32_32x32x16_bf16 v[64:79], v[100:103], v[192:195], v[64:79]
	ds_read_b64_tr_b16 v[192:193], v196 offset:0x1200
	ds_read_b64_tr_b16 v[194:195], v196 offset:0x1a00
	v_mfma_f32_32x32x16_bf16 v[64:79], v[104:107], v[228:231], v[64:79]
	ds_read_b64_tr_b16 v[228:229], v196 offset:0x2200
	ds_read_b64_tr_b16 v[230:231], v196 offset:0x2a00
	ds_read_b64_tr_b16 v[236:237], v196 offset:0x3200
	ds_read_b64_tr_b16 v[238:239], v196 offset:0x3a00
	s_waitcnt lgkmcnt(0)
	v_mfma_f32_32x32x16_bf16 v[64:79], v[108:111], v[232:235], v[64:79]
	v_mfma_f32_32x32x16_bf16 v[48:63], v[96:99], v[188:191], v[48:63]
	ds_read_b64_tr_b16 v[188:189], v196 offset:0x400
	ds_read_b64_tr_b16 v[190:191], v196 offset:0xc00
	v_mfma_f32_32x32x16_bf16 v[48:63], v[100:103], v[192:195], v[48:63]
	ds_read_b64_tr_b16 v[192:193], v196 offset:0x1400
	ds_read_b64_tr_b16 v[194:195], v196 offset:0x1c00
	v_mfma_f32_32x32x16_bf16 v[48:63], v[104:107], v[228:231], v[48:63]
	ds_read_b64_tr_b16 v[228:229], v196 offset:0x2400
	ds_read_b64_tr_b16 v[230:231], v196 offset:0x2c00
	ds_read_b64_tr_b16 v[232:233], v196 offset:0x3400
	ds_read_b64_tr_b16 v[234:235], v196 offset:0x3c00
	s_waitcnt lgkmcnt(0)
	v_mfma_f32_32x32x16_bf16 v[48:63], v[108:111], v[236:239], v[48:63]
	v_mfma_f32_32x32x16_bf16 v[32:47], v[96:99], v[188:191], v[32:47]
	ds_read_b64_tr_b16 v[188:189], v196 offset:0x600
	ds_read_b64_tr_b16 v[190:191], v196 offset:0xe00
	v_mfma_f32_32x32x16_bf16 v[32:47], v[100:103], v[192:195], v[32:47]
	ds_read_b64_tr_b16 v[192:193], v196 offset:0x1600
	ds_read_b64_tr_b16 v[194:195], v196 offset:0x1e00
	ds_read_b64_tr_b16 v[244:245], v196 offset:0x2600
	ds_read_b64_tr_b16 v[246:247], v196 offset:0x2e00
	ds_read_b64_tr_b16 v[248:249], v196 offset:0x3600
	ds_read_b64_tr_b16 v[250:251], v196 offset:0x3e00
	s_waitcnt lgkmcnt(0)
	v_mfma_f32_32x32x16_bf16 v[32:47], v[104:107], v[228:231], v[32:47]
	v_mfma_f32_32x32x16_bf16 v[32:47], v[108:111], v[232:235], v[32:47]
	v_mfma_f32_32x32x16_bf16 v[16:31], v[96:99], v[188:191], v[16:31]
	v_exp_f32_e32 v240, v112
	v_exp_f32_e32 v242, v113
	v_exp_f32_e32 v238, v114
	v_exp_f32_e32 v241, v115
	v_exp_f32_e32 v236, v116
	v_exp_f32_e32 v239, v117
	v_exp_f32_e32 v235, v118
	v_mfma_f32_32x32x16_bf16 v[16:31], v[100:103], v[192:195], v[16:31]
	v_exp_f32_e32 v237, v119
	v_exp_f32_e32 v232, v120
	v_exp_f32_e32 v234, v121
	v_exp_f32_e32 v230, v122
	v_exp_f32_e32 v233, v123
	v_exp_f32_e32 v228, v124
	v_exp_f32_e32 v231, v125
	v_mfma_f32_32x32x16_bf16 v[16:31], v[104:107], v[244:247], v[16:31]
	v_exp_f32_e32 v227, v126
	v_exp_f32_e32 v229, v127
	s_add_i32 s48, s48, 2
	v_mfma_f32_32x32x16_bf16 v[16:31], v[108:111], v[248:251], v[16:31]
	s_mov_b32 s54, s49
	s_mov_b32 s49, s50
	s_cmp_gt_u32 s48, 28
	s_mov_b32 s50, s51
	s_cbranch_scc0 .LBB0_719
	s_waitcnt vmcnt(0)
	s_waitcnt lgkmcnt(0)
	v_and_b32_e32 v96, 0x3fffffc0, v210
	v_mov_b32_e32 v97, 0x1e000
	v_lshl_add_u32 v178, v96, 2, v97
	s_barrier
	s_setprio 1
	v_or_b32_e32 v179, 0xe000, v213
	v_add_u32_e32 v96, v213, v214
	v_add_u32_e32 v100, v179, v214
	ds_read_b128 v[96:99], v96 offset:57344
	ds_read_b128 v[180:183], v100 offset:8192
	s_waitcnt lgkmcnt(0)
	v_mfma_f32_32x32x16_bf16 v[112:127], v[96:99], v[128:131], v[0:15]
	v_mfma_f32_32x32x16_bf16 v[96:111], v[180:183], v[128:131], v[0:15]
	v_add_u32_e32 v128, v213, v215
	v_add_u32_e32 v180, v179, v215
	ds_read_b128 v[128:131], v128 offset:57344
	ds_read_b128 v[180:183], v180 offset:8192
	s_waitcnt lgkmcnt(0)
	v_mfma_f32_32x32x16_bf16 v[112:127], v[128:131], v[132:135], v[112:127]
	v_add_u32_e32 v128, v213, v216
	ds_read_b128 v[128:131], v128 offset:57344
	v_mfma_f32_32x32x16_bf16 v[96:111], v[180:183], v[132:135], v[96:111]
	v_add_u32_e32 v132, v179, v216
	ds_read_b128 v[132:135], v132 offset:8192
	s_waitcnt lgkmcnt(0)
	v_mfma_f32_32x32x16_bf16 v[112:127], v[128:131], v[136:139], v[112:127]
	v_add_u32_e32 v128, v213, v217
	ds_read_b128 v[128:131], v128 offset:57344
	v_mfma_f32_32x32x16_bf16 v[96:111], v[132:135], v[136:139], v[96:111]
	v_add_u32_e32 v132, v179, v217
	ds_read_b128 v[132:135], v132 offset:8192
	v_or_b32_e32 v136, 0x12000, v222
	s_waitcnt lgkmcnt(0)
	v_mfma_f32_32x32x16_bf16 v[112:127], v[128:131], v[140:143], v[112:127]
	v_add_u32_e32 v128, v213, v218
	ds_read_b128 v[128:131], v128 offset:57344
	v_mfma_f32_32x32x16_bf16 v[96:111], v[132:135], v[140:143], v[96:111]
	v_add_u32_e32 v132, v179, v218
	ds_read_b128 v[132:135], v132 offset:8192
	s_waitcnt lgkmcnt(0)
	v_mfma_f32_32x32x16_bf16 v[112:127], v[128:131], v[144:147], v[112:127]
	v_add_u32_e32 v128, v213, v219
	ds_read_b128 v[128:131], v128 offset:57344
	v_mfma_f32_32x32x16_bf16 v[96:111], v[132:135], v[144:147], v[96:111]
	v_add_u32_e32 v132, v179, v219
	ds_read_b128 v[132:135], v132 offset:8192
	s_waitcnt lgkmcnt(0)
	v_mfma_f32_32x32x16_bf16 v[112:127], v[128:131], v[148:151], v[112:127]
	v_add_u32_e32 v128, v213, v220
	ds_read_b128 v[128:131], v128 offset:57344
	v_mfma_f32_32x32x16_bf16 v[96:111], v[132:135], v[148:151], v[96:111]
	v_add_u32_e32 v132, v179, v220
	ds_read_b128 v[132:135], v132 offset:8192
	s_waitcnt lgkmcnt(0)
	v_mfma_f32_32x32x16_bf16 v[112:127], v[128:131], v[152:155], v[112:127]
	v_add_u32_e32 v128, v213, v221
	ds_read_b128 v[128:131], v128 offset:57344
	v_mfma_f32_32x32x16_bf16 v[96:111], v[132:135], v[152:155], v[96:111]
	v_add_u32_e32 v132, v179, v221
	ds_read_b128 v[132:135], v132 offset:8192
	s_waitcnt lgkmcnt(0)
; #define SBAR() __builtin_amdgcn_sched_barrier(0)
; __device__ __forceinline__ void finishSM(f32x16& p0, f32x16& p1, float& l_reg, bf16x8& pa0, bf16x8& pa1, bf16x8& pa2, bf16x8& pa3) {
; #pragma unroll
;   for (int r = 0; r < 16; ++r) p1[r] = __builtin_amdgcn_exp2f(p1[r]);
;   float ps = 0;
; #pragma unroll
;   for (int r = 0; r < 16; ++r) ps += p0[r];
; #pragma unroll
;   for (int r = 0; r < 16; ++r) ps += p1[r];
;   { auto rr = __builtin_amdgcn_permlane32_swap(__float_as_uint(ps), __float_as_uint(ps), false, false);
;     ps = __uint_as_float(rr[0]) + __uint_as_float(rr[1]); }
;   l_reg += ps;
;     ...
;   PK4(p0, 0, pa0); PK4(p0, 8, pa1); PK4(p1, 0, pa2); PK4(p1, 8, pa3);
;     ...
; }
; template <int OFF> __device__ __forceinline__ s16x4 tr_read(int vb) {
;   s16x4 r; asm volatile("ds_read_b64_tr_b16 %0, %1 offset:%2" : "=&v"(r) : "v"(vb), "i"(OFF) : "memory"); return r;
; }
; template <int D0> __device__ __forceinline__ void pv_one(f32x16& od, int vb, bf16x8 pa0, bf16x8 pa1, bf16x8 pa2, bf16x8 pa3) {
;   const s16x4 l0 = tr_read<v_rd_off(D0, 0, 0)>(vb), h0 = tr_read<v_rd_off(D0, 0, 1)>(vb), l1 = tr_read<v_rd_off(D0, 1, 0)>(vb), h1 = tr_read<v_rd_off(D0, 1, 1)>(vb);
;   const s16x4 l2 = tr_read<v_rd_off(D0, 2, 0)>(vb), h2 = tr_read<v_rd_off(D0, 2, 1)>(vb), l3 = tr_read<v_rd_off(D0, 3, 0)>(vb), h3 = tr_read<v_rd_off(D0, 3, 1)>(vb);
;   asm volatile("s_waitcnt lgkmcnt(0)" ::: "memory"); SBAR();
;     ...
;   od = __builtin_amdgcn_mfma_f32_32x32x16_bf16(pa0, PK(l0, h0), od, 0, 0, 0);
;   od = __builtin_amdgcn_mfma_f32_32x32x16_bf16(pa1, PK(l1, h1), od, 0, 0, 0);
;   od = __builtin_amdgcn_mfma_f32_32x32x16_bf16(pa2, PK(l2, h2), od, 0, 0, 0);
;   od = __builtin_amdgcn_mfma_f32_32x32x16_bf16(pa3, PK(l3, h3), od, 0, 0, 0);
;     ...
; }
; __device__ __forceinline__ void pv_d0(f32x16* o, int vb, bf16x8 pa0, bf16x8 pa1, bf16x8 pa2, bf16x8 pa3) {
;   pv_one<0>(o[0], vb, pa0, pa1, pa2, pa3); pv_one<1>(o[1], vb, pa0, pa1, pa2, pa3); pv_one<2>(o[2], vb, pa0, pa1, pa2, pa3); pv_one<3>(o[3], vb, pa0, pa1, pa2, pa3);
; }
	v_mfma_f32_32x32x16_bf16 v[112:127], v[128:131], v[156:159], v[112:127]
	v_mfma_f32_32x32x16_bf16 v[96:111], v[132:135], v[156:159], v[96:111]
	v_add_u32_e32 v132, v136, v223
	ds_read_b128 v[128:131], v132
	ds_read_b128 v[132:135], v132 offset:4096
	s_waitcnt lgkmcnt(0)
	v_mfma_f32_32x32x16_bf16 v[112:127], v[128:131], v[164:167], v[112:127]
	v_mfma_f32_32x32x16_bf16 v[96:111], v[132:135], v[164:167], v[96:111]
	v_add_u32_e32 v132, v136, v224
	ds_read_b128 v[128:131], v132
	ds_read_b128 v[132:135], v132 offset:4096
	s_waitcnt lgkmcnt(0)
	v_mfma_f32_32x32x16_bf16 v[112:127], v[128:131], v[172:175], v[112:127]
	v_mfma_f32_32x32x16_bf16 v[96:111], v[132:135], v[172:175], v[96:111]
	v_add_u32_e32 v132, v136, v225
	ds_read_b128 v[128:131], v132
	ds_read_b128 v[132:135], v132 offset:4096
	s_waitcnt lgkmcnt(0)
	v_mfma_f32_32x32x16_bf16 v[112:127], v[128:131], v[160:163], v[112:127]
	v_mfma_f32_32x32x16_bf16 v[96:111], v[132:135], v[160:163], v[96:111]
	v_add_u32_e32 v132, v136, v226
	ds_read_b128 v[128:131], v132
	ds_read_b128 v[132:135], v132 offset:4096
	s_waitcnt lgkmcnt(0)
	v_mfma_f32_32x32x16_bf16 v[112:127], v[128:131], v[168:171], v[112:127]
	v_mfma_f32_32x32x16_bf16 v[96:111], v[132:135], v[168:171], v[96:111]
	s_setprio 0
	v_exp_f32_e32 v128, v80
	v_add_f32_e32 v80, 0, v240
	v_add_f32_e32 v80, v242, v80
	v_add_f32_e32 v80, v238, v80
	v_add_f32_e32 v80, v241, v80
	v_add_f32_e32 v80, v236, v80
	v_add_f32_e32 v80, v239, v80
	v_add_f32_e32 v80, v235, v80
	v_add_f32_e32 v80, v237, v80
	v_add_f32_e32 v80, v232, v80
	v_add_f32_e32 v80, v234, v80
	v_add_f32_e32 v80, v230, v80
	v_add_f32_e32 v80, v233, v80
	v_add_f32_e32 v80, v228, v80
	v_exp_f32_e32 v81, v81
	v_add_f32_e32 v80, v231, v80
	v_exp_f32_e32 v129, v82
	v_add_f32_e32 v80, v227, v80
	v_exp_f32_e32 v83, v83
	v_add_f32_e32 v80, v229, v80
	v_exp_f32_e32 v130, v84
	v_add_f32_e32 v80, v128, v80
	v_exp_f32_e32 v131, v85
	v_add_f32_e32 v80, v81, v80
	v_exp_f32_e32 v132, v86
	v_add_f32_e32 v80, v129, v80
	v_exp_f32_e32 v133, v87
	v_add_f32_e32 v80, v83, v80
	v_exp_f32_e32 v134, v88
	v_add_f32_e32 v80, v130, v80
	v_exp_f32_e32 v135, v89
	v_add_f32_e32 v80, v131, v80
	v_exp_f32_e32 v136, v90
	v_add_f32_e32 v80, v132, v80
	v_exp_f32_e32 v137, v91
	v_add_f32_e32 v80, v133, v80
	v_exp_f32_e32 v138, v92
	v_add_f32_e32 v80, v134, v80
	v_exp_f32_e32 v139, v93
	v_add_f32_e32 v80, v135, v80
	v_exp_f32_e32 v140, v94
	v_add_f32_e32 v80, v136, v80
	v_exp_f32_e32 v141, v95
	v_add_f32_e32 v80, v137, v80
	v_add_f32_e32 v80, v138, v80
	v_add_f32_e32 v80, v139, v80
	v_add_f32_e32 v80, v140, v80
	v_add_f32_e32 v80, v141, v80
	v_mov_b32_e32 v82, v80
	s_nop 1
	v_permlane32_swap_b32_e32 v80, v82
	s_nop 0
	v_cvt_pk_bf16_f32 v84, v240, v242
	s_nop 0
	v_cvt_pk_bf16_f32 v85, v238, v241
	s_nop 0
	v_cvt_pk_bf16_f32 v86, v236, v239
	s_nop 0
	v_cvt_pk_bf16_f32 v87, v235, v237
	s_nop 0
	v_cvt_pk_bf16_f32 v88, v232, v234
	s_nop 0
	v_cvt_pk_bf16_f32 v89, v230, v233
	s_nop 0
	v_cvt_pk_bf16_f32 v90, v228, v231
	s_nop 0
	v_cvt_pk_bf16_f32 v91, v227, v229
	s_nop 0
	v_cvt_pk_bf16_f32 v92, v128, v81
	s_nop 0
	v_cvt_pk_bf16_f32 v93, v129, v83
	s_nop 0
	v_cvt_pk_bf16_f32 v94, v130, v131
	s_nop 0
	v_cvt_pk_bf16_f32 v95, v132, v133
	s_nop 0
	v_cvt_pk_bf16_f32 v128, v134, v135
	s_nop 0
	v_cvt_pk_bf16_f32 v129, v136, v137
	s_nop 0
	v_cvt_pk_bf16_f32 v130, v138, v139
	s_nop 0
	v_cvt_pk_bf16_f32 v131, v140, v141
	s_nop 0
	v_permlane32_swap_b32_e32 v84, v86
	v_permlane32_swap_b32_e32 v85, v87
	v_permlane32_swap_b32_e32 v88, v90
	v_permlane32_swap_b32_e32 v89, v91
	v_permlane32_swap_b32_e32 v92, v94
	v_permlane32_swap_b32_e32 v93, v95
	v_permlane32_swap_b32_e32 v128, v130
	v_permlane32_swap_b32_e32 v129, v131
	ds_read_b64_tr_b16 v[132:133], v212 offset:0
	ds_read_b64_tr_b16 v[134:135], v212 offset:0x800
	ds_read_b64_tr_b16 v[136:137], v212 offset:0x1000
	ds_read_b64_tr_b16 v[138:139], v212 offset:0x1800
	ds_read_b64_tr_b16 v[140:141], v212 offset:0x2000
	ds_read_b64_tr_b16 v[142:143], v212 offset:0x2800
	ds_read_b64_tr_b16 v[144:145], v212 offset:0x3000
	ds_read_b64_tr_b16 v[146:147], v212 offset:0x3800
	s_waitcnt lgkmcnt(0)
	s_nop 0
	v_mfma_f32_32x32x16_bf16 v[64:79], v[84:87], v[132:135], v[64:79]
	ds_read_b64_tr_b16 v[132:133], v212 offset:0x200
	ds_read_b64_tr_b16 v[134:135], v212 offset:0xa00
	v_mfma_f32_32x32x16_bf16 v[64:79], v[88:91], v[136:139], v[64:79]
	ds_read_b64_tr_b16 v[136:137], v212 offset:0x1200
	ds_read_b64_tr_b16 v[138:139], v212 offset:0x1a00
	v_mfma_f32_32x32x16_bf16 v[64:79], v[92:95], v[140:143], v[64:79]
	ds_read_b64_tr_b16 v[140:141], v212 offset:0x2200
	ds_read_b64_tr_b16 v[142:143], v212 offset:0x2a00
	ds_read_b64_tr_b16 v[148:149], v212 offset:0x3200
	ds_read_b64_tr_b16 v[150:151], v212 offset:0x3a00
	s_waitcnt lgkmcnt(0)
	v_mfma_f32_32x32x16_bf16 v[64:79], v[128:131], v[144:147], v[64:79]
	v_mfma_f32_32x32x16_bf16 v[48:63], v[84:87], v[132:135], v[48:63]
	ds_read_b64_tr_b16 v[132:133], v212 offset:0x400
	ds_read_b64_tr_b16 v[134:135], v212 offset:0xc00
	v_mfma_f32_32x32x16_bf16 v[48:63], v[88:91], v[136:139], v[48:63]
	ds_read_b64_tr_b16 v[136:137], v212 offset:0x1400
	ds_read_b64_tr_b16 v[138:139], v212 offset:0x1c00
	v_mfma_f32_32x32x16_bf16 v[48:63], v[92:95], v[140:143], v[48:63]
	ds_read_b64_tr_b16 v[140:141], v212 offset:0x2400
	ds_read_b64_tr_b16 v[142:143], v212 offset:0x2c00
	ds_read_b64_tr_b16 v[144:145], v212 offset:0x3400
	ds_read_b64_tr_b16 v[146:147], v212 offset:0x3c00
	s_waitcnt lgkmcnt(0)
; __device__ __forceinline__ void finishSM(f32x16& p0, f32x16& p1, float& l_reg, bf16x8& pa0, bf16x8& pa1, bf16x8& pa2, bf16x8& pa3) {
; #pragma unroll
;   for (int r = 0; r < 16; ++r) p1[r] = __builtin_amdgcn_exp2f(p1[r]);
;   float ps = 0;
; #pragma unroll
;   for (int r = 0; r < 16; ++r) ps += p0[r];
; #pragma unroll
;   for (int r = 0; r < 16; ++r) ps += p1[r];
;   { auto rr = __builtin_amdgcn_permlane32_swap(__float_as_uint(ps), __float_as_uint(ps), false, false);
;     ps = __uint_as_float(rr[0]) + __uint_as_float(rr[1]); }
;   l_reg += ps;
;     ...
;   PK4(p0, 0, pa0); PK4(p0, 8, pa1); PK4(p1, 0, pa2); PK4(p1, 8, pa3);
;     ...
; }
; __device__ __forceinline__ void qkt(f32x16& p0, f32x16& p1, const char* Ks, const bf16x8* qr, int r32, int hi, float negM) {
; #pragma unroll
;   for (int r = 0; r < 16; ++r) { p0[r] = negM; p1[r] = negM; }
;   __builtin_amdgcn_s_setprio(1);
;   const char* kn = Ks + r32 * 256; const int xn = r32 & 15;
; #pragma unroll
;   for (int d0 = 0; d0 < 8; ++d0) { const int off = ((d0 * 2 + hi) ^ xn) << 4;
;     bf16x8 b0 = *reinterpret_cast<const bf16x8*>(kn + off);
;     bf16x8 b1 = *reinterpret_cast<const bf16x8*>(kn + 32 * 256 + off);
;     p0 = __builtin_amdgcn_mfma_f32_32x32x16_bf16(b0, qr[d0], p0, 0, 0, 0);
;     p1 = __builtin_amdgcn_mfma_f32_32x32x16_bf16(b1, qr[d0], p1, 0, 0, 0); }
;   const char* kr = Ks + KROPE_OFF + r32 * 128; const int xr = (r32 >> 1) & 7;
; #pragma unroll
;   for (int d0 = 8; d0 < 12; ++d0) { const int off = (((d0 - 8) * 2 + hi) ^ xr) << 4;
;     bf16x8 b0 = *reinterpret_cast<const bf16x8*>(kr + off);
;     bf16x8 b1 = *reinterpret_cast<const bf16x8*>(kr + 32 * 128 + off);
;     p0 = __builtin_amdgcn_mfma_f32_32x32x16_bf16(b0, qr[d0], p0, 0, 0, 0);
;     p1 = __builtin_amdgcn_mfma_f32_32x32x16_bf16(b1, qr[d0], p1, 0, 0, 0); }
;   __builtin_amdgcn_s_setprio(0);
; }
; __device__ __forceinline__ int v_st(int k, int c) { const int kk = (k & ~0xC) | ((k & 4) << 1) | ((k & 8) >> 1); return ((kk >> 3) * 4 + (c >> 5)) * 512 + ((kk & 7) * 32 + (c & 31)) * 2; }
; __device__ __forceinline__ int v_rd_base(int lane) { return ((lane & 3) << 3) | (((lane >> 2) & 3) << 6) | (((lane >> 4) & 1) << 5) | (((lane >> 5) & 1) << 8); }
; template <int OFF> __device__ __forceinline__ s16x4 tr_read(int vb) {
;   s16x4 r; asm volatile("ds_read_b64_tr_b16 %0, %1 offset:%2" : "=&v"(r) : "v"(vb), "i"(OFF) : "memory"); return r;
; }
	v_mfma_f32_32x32x16_bf16 v[48:63], v[128:131], v[148:151], v[48:63]
	v_mfma_f32_32x32x16_bf16 v[32:47], v[84:87], v[132:135], v[32:47]
	ds_read_b64_tr_b16 v[132:133], v212 offset:0x600
	ds_read_b64_tr_b16 v[134:135], v212 offset:0xe00
	v_mfma_f32_32x32x16_bf16 v[32:47], v[88:91], v[136:139], v[32:47]
	ds_read_b64_tr_b16 v[136:137], v212 offset:0x1600
	ds_read_b64_tr_b16 v[138:139], v212 offset:0x1e00
	v_mfma_f32_32x32x16_bf16 v[32:47], v[92:95], v[140:143], v[32:47]
	ds_read_b64_tr_b16 v[140:141], v212 offset:0x2600
	ds_read_b64_tr_b16 v[142:143], v212 offset:0x2e00
	ds_read_b64_tr_b16 v[148:149], v212 offset:0x3600
	ds_read_b64_tr_b16 v[150:151], v212 offset:0x3e00
	s_waitcnt lgkmcnt(0)
	v_mfma_f32_32x32x16_bf16 v[32:47], v[128:131], v[144:147], v[32:47]
	v_exp_f32_e32 v112, v112
	v_exp_f32_e32 v113, v113
	v_exp_f32_e32 v114, v114
	v_exp_f32_e32 v115, v115
	v_exp_f32_e32 v116, v116
	v_mfma_f32_32x32x16_bf16 v[16:31], v[84:87], v[132:135], v[16:31]
	v_add_f32_e32 v81, 0, v112
	v_exp_f32_e32 v117, v117
	v_add_f32_e32 v81, v113, v81
	v_exp_f32_e32 v87, v118
	v_add_f32_e32 v81, v114, v81
	v_exp_f32_e32 v118, v119
	v_add_f32_e32 v81, v115, v81
	v_exp_f32_e32 v119, v120
	v_add_f32_e32 v81, v116, v81
	v_exp_f32_e32 v120, v121
	v_add_f32_e32 v81, v117, v81
	v_exp_f32_e32 v121, v122
	v_add_f32_e32 v81, v87, v81
	v_exp_f32_e32 v122, v123
	v_add_f32_e32 v81, v118, v81
	v_exp_f32_e32 v123, v124
	v_mfma_f32_32x32x16_bf16 v[16:31], v[88:91], v[136:139], v[16:31]
	v_add_f32_e32 v81, v119, v81
	v_exp_f32_e32 v90, v125
	v_add_f32_e32 v81, v120, v81
	v_exp_f32_e32 v91, v126
	v_add_f32_e32 v81, v121, v81
	v_exp_f32_e32 v124, v127
	v_add_f32_e32 v81, v122, v81
	v_exp_f32_e32 v96, v96
	v_add_f32_e32 v81, v123, v81
	v_exp_f32_e32 v97, v97
	v_add_f32_e32 v81, v90, v81
	v_exp_f32_e32 v98, v98
	v_add_f32_e32 v81, v91, v81
	v_exp_f32_e32 v99, v99
	v_add_f32_e32 v81, v124, v81
	v_mfma_f32_32x32x16_bf16 v[16:31], v[92:95], v[140:143], v[16:31]
	v_exp_f32_e32 v94, v100
	v_add_f32_e32 v81, v96, v81
	v_exp_f32_e32 v95, v101
	v_add_f32_e32 v81, v97, v81
	v_exp_f32_e32 v100, v102
	v_add_f32_e32 v81, v98, v81
	v_exp_f32_e32 v101, v103
	v_add_f32_e32 v81, v99, v81
	v_exp_f32_e32 v102, v104
	v_add_f32_e32 v81, v94, v81
	v_exp_f32_e32 v103, v105
	v_add_f32_e32 v81, v95, v81
	v_exp_f32_e32 v104, v106
	v_add_f32_e32 v81, v100, v81
	v_exp_f32_e32 v105, v107
	v_add_f32_e32 v81, v101, v81
	v_exp_f32_e32 v106, v108
	v_add_f32_e32 v81, v102, v81
	v_exp_f32_e32 v107, v109
	v_add_f32_e32 v81, v103, v81
	v_mfma_f32_32x32x16_bf16 v[16:31], v[128:131], v[148:151], v[16:31]
	v_exp_f32_e32 v108, v110
	v_add_f32_e32 v81, v104, v81
	v_exp_f32_e32 v109, v111
	v_add_f32_e32 v81, v105, v81
	v_add_f32_e32 v81, v106, v81
	v_add_f32_e32 v81, v107, v81
	v_add_f32_e32 v81, v108, v81
	v_add_f32_e32 v81, v109, v81
	v_mov_b32_e32 v83, v81
	s_nop 1
	v_permlane32_swap_b32_e32 v81, v83
	s_nop 0
	v_cvt_pk_bf16_f32 v84, v112, v113
	s_nop 0
	v_cvt_pk_bf16_f32 v85, v114, v115
	s_nop 0
	v_cvt_pk_bf16_f32 v86, v116, v117
	s_nop 0
	v_cvt_pk_bf16_f32 v87, v87, v118
	s_nop 0
	v_cvt_pk_bf16_f32 v88, v119, v120
	s_nop 0
	v_cvt_pk_bf16_f32 v89, v121, v122
	s_nop 0
	v_cvt_pk_bf16_f32 v90, v123, v90
	s_nop 0
	v_cvt_pk_bf16_f32 v91, v91, v124
	s_nop 0
	v_cvt_pk_bf16_f32 v92, v96, v97
	s_nop 0
	v_cvt_pk_bf16_f32 v93, v98, v99
	s_nop 0
	v_cvt_pk_bf16_f32 v94, v94, v95
	s_nop 0
	v_cvt_pk_bf16_f32 v95, v100, v101
	s_nop 0
	v_cvt_pk_bf16_f32 v96, v102, v103
	s_nop 0
	v_cvt_pk_bf16_f32 v97, v104, v105
	s_nop 0
	v_cvt_pk_bf16_f32 v98, v106, v107
	s_nop 0
	v_cvt_pk_bf16_f32 v99, v108, v109
	s_nop 0
	v_permlane32_swap_b32_e32 v84, v86
	v_permlane32_swap_b32_e32 v85, v87
	v_permlane32_swap_b32_e32 v88, v90
	v_permlane32_swap_b32_e32 v89, v91
	v_permlane32_swap_b32_e32 v92, v94
	v_permlane32_swap_b32_e32 v93, v95
	v_permlane32_swap_b32_e32 v96, v98
	v_permlane32_swap_b32_e32 v97, v99
	v_or_b32_e32 v120, 0xa000, v212
	ds_read_b64_tr_b16 v[100:101], v120 offset:0
	ds_read_b64_tr_b16 v[102:103], v120 offset:0x800
	ds_read_b64_tr_b16 v[104:105], v120 offset:0x1000
	ds_read_b64_tr_b16 v[106:107], v120 offset:0x1800
	ds_read_b64_tr_b16 v[108:109], v120 offset:0x2000
	ds_read_b64_tr_b16 v[110:111], v120 offset:0x2800
	ds_read_b64_tr_b16 v[112:113], v120 offset:0x3000
	ds_read_b64_tr_b16 v[114:115], v120 offset:0x3800
	s_waitcnt lgkmcnt(0)
	s_nop 0
	v_mfma_f32_32x32x16_bf16 v[64:79], v[84:87], v[100:103], v[64:79]
	ds_read_b64_tr_b16 v[100:101], v120 offset:0x200
	ds_read_b64_tr_b16 v[102:103], v120 offset:0xa00
	v_mfma_f32_32x32x16_bf16 v[64:79], v[88:91], v[104:107], v[64:79]
	ds_read_b64_tr_b16 v[104:105], v120 offset:0x1200
	ds_read_b64_tr_b16 v[106:107], v120 offset:0x1a00
	v_mfma_f32_32x32x16_bf16 v[64:79], v[92:95], v[108:111], v[64:79]
	ds_read_b64_tr_b16 v[108:109], v120 offset:0x2200
	ds_read_b64_tr_b16 v[110:111], v120 offset:0x2a00
	ds_read_b64_tr_b16 v[116:117], v120 offset:0x3200
	ds_read_b64_tr_b16 v[118:119], v120 offset:0x3a00
	s_waitcnt lgkmcnt(0)
	v_mfma_f32_32x32x16_bf16 v[64:79], v[96:99], v[112:115], v[64:79]
	v_mfma_f32_32x32x16_bf16 v[48:63], v[84:87], v[100:103], v[48:63]
	ds_read_b64_tr_b16 v[100:101], v120 offset:0x400
	ds_read_b64_tr_b16 v[102:103], v120 offset:0xc00
	v_mfma_f32_32x32x16_bf16 v[48:63], v[88:91], v[104:107], v[48:63]
	ds_read_b64_tr_b16 v[104:105], v120 offset:0x1400
	ds_read_b64_tr_b16 v[106:107], v120 offset:0x1c00
	v_mfma_f32_32x32x16_bf16 v[48:63], v[92:95], v[108:111], v[48:63]
	ds_read_b64_tr_b16 v[108:109], v120 offset:0x2400
	ds_read_b64_tr_b16 v[110:111], v120 offset:0x2c00
	ds_read_b64_tr_b16 v[112:113], v120 offset:0x3400
	ds_read_b64_tr_b16 v[114:115], v120 offset:0x3c00
	s_waitcnt lgkmcnt(0)
	v_mfma_f32_32x32x16_bf16 v[48:63], v[96:99], v[116:119], v[48:63]
	v_mfma_f32_32x32x16_bf16 v[32:47], v[84:87], v[100:103], v[32:47]
	ds_read_b64_tr_b16 v[100:101], v120 offset:0x600
	ds_read_b64_tr_b16 v[102:103], v120 offset:0xe00
	v_mfma_f32_32x32x16_bf16 v[32:47], v[88:91], v[104:107], v[32:47]
	ds_read_b64_tr_b16 v[104:105], v120 offset:0x1600
	ds_read_b64_tr_b16 v[106:107], v120 offset:0x1e00
	v_mfma_f32_32x32x16_bf16 v[32:47], v[92:95], v[108:111], v[32:47]
	ds_read_b64_tr_b16 v[108:109], v120 offset:0x2600
	ds_read_b64_tr_b16 v[110:111], v120 offset:0x2e00
	ds_read_b64_tr_b16 v[116:117], v120 offset:0x3600
	ds_read_b64_tr_b16 v[118:119], v120 offset:0x3e00
	s_waitcnt lgkmcnt(0)
	v_mfma_f32_32x32x16_bf16 v[32:47], v[96:99], v[112:115], v[32:47]
	v_mfma_f32_32x32x16_bf16 v[16:31], v[84:87], v[100:103], v[16:31]
	v_cmp_gt_u32_e32 vcc, 32, v209
	v_mfma_f32_32x32x16_bf16 v[16:31], v[88:91], v[104:107], v[16:31]
	v_mfma_f32_32x32x16_bf16 v[16:31], v[92:95], v[108:111], v[16:31]
	v_mfma_f32_32x32x16_bf16 v[16:31], v[96:99], v[116:119], v[16:31]
	s_and_saveexec_b64 s[48:49], vcc
	s_cbranch_execz .LBB0_717
	v_pk_add_f32 v[80:81], v[80:81], v[82:83]
	v_lshl_add_u32 v84, v206, 2, v178
	v_add_f32_e32 v80, v176, v80
	v_add_f32_e32 v80, v80, v81
	ds_write_b32 v84, v80
	s_branch .LBB0_717
